# PEEL: first K-loop iteration of the five GEMM phases peeled with C = 0 MFMAs instead of clearing 128 accumulator registers per tile with v_mov (on SO7)
# speedup vs baseline: 1.0089x; 1.0089x over previous
.LBB0_212:
	s_ashr_i32 s27, s26, 31
	s_lshl_b64 s[30:31], s[26:27], 19
	s_ashr_i32 s25, s24, 31
	v_lshl_add_u64 v[148:149], v[130:131], 0, s[30:31]
	s_lshl_b64 s[30:31], s[24:25], 19
	v_lshl_add_u64 v[150:151], v[132:133], 0, s[30:31]
	v_cndmask_b32_e64 v152, v2, v150, s[4:5]
	v_lshl_add_u64 v[156:157], v[2:3], 0, s[20:21]
	v_mov_b32_e32 v2, 0
	v_cndmask_b32_e64 v1, v5, v149, s[4:5]
	v_cndmask_b32_e64 v138, v4, v148, s[4:5]
	v_cndmask_b32_e64 v153, v3, v151, s[4:5]
	v_lshl_add_u64 v[154:155], v[4:5], 0, s[16:17]
	s_mov_b32 s7, -2
	ds_read_b128 v[168:171], v160
	ds_read_b128 v[172:175], v160 offset:1024
	ds_read_b128 v[176:179], v160 offset:2048
	ds_read_b128 v[180:183], v160 offset:3072
	ds_read_b128 v[184:187], v161
	ds_read_b128 v[188:191], v161 offset:1024
	ds_read_b128 v[192:195], v161 offset:2048
	ds_read_b128 v[196:199], v161 offset:3072
	s_cmp_eq_u32 s7, 12
	v_lshl_add_u64 v[200:201], v[154:155], 0, s[22:23]
	s_cselect_b64 vcc, -1, 0
	v_cndmask_b32_e32 v233, v201, v1, vcc
	v_cndmask_b32_e32 v232, v200, v138, vcc
	v_cndmask_b32_e32 v235, v157, v153, vcc
	v_cndmask_b32_e32 v234, v156, v152, vcc
	s_mov_b32 m0, s42
	v_lshl_add_u64 v[236:237], v[154:155], 0, v[140:141]
	ds_read_b128 v[200:203], v162
	ds_read_b128 v[204:207], v162 offset:1024
	ds_read_b128 v[208:211], v162 offset:2048
	ds_read_b128 v[212:215], v162 offset:3072
	ds_read_b128 v[216:219], v162 offset:4096
	ds_read_b128 v[220:223], v162 offset:5120
	ds_read_b128 v[224:227], v162 offset:6144
	ds_read_b128 v[228:231], v162 offset:7168
	global_load_lds_dwordx4 v[236:237], off
	v_lshl_add_u64 v[236:237], v[154:155], 0, v[142:143]
	s_mov_b32 m0, s43
	s_nop 0
	global_load_lds_dwordx4 v[236:237], off
	s_waitcnt vmcnt(8)
	s_waitcnt lgkmcnt(0)
	s_barrier
	s_setprio 1
	s_waitcnt lgkmcnt(0)
	v_mfma_f32_16x16x32_bf16 v[126:129], v[168:171], v[200:203], 0
	v_mfma_f32_16x16x32_bf16 v[122:125], v[176:179], v[200:203], 0
	v_mfma_f32_16x16x32_bf16 v[110:113], v[168:171], v[208:211], 0
	v_mfma_f32_16x16x32_bf16 v[106:109], v[176:179], v[208:211], 0
	v_mfma_f32_16x16x32_bf16 v[94:97], v[168:171], v[216:219], 0
	v_mfma_f32_16x16x32_bf16 v[90:93], v[176:179], v[216:219], 0
	v_mfma_f32_16x16x32_bf16 v[78:81], v[168:171], v[224:227], 0
	v_mfma_f32_16x16x32_bf16 v[74:77], v[176:179], v[224:227], 0
	v_mfma_f32_16x16x32_bf16 v[126:129], v[172:175], v[204:207], v[126:129]
	v_mfma_f32_16x16x32_bf16 v[122:125], v[180:183], v[204:207], v[122:125]
	v_mfma_f32_16x16x32_bf16 v[110:113], v[172:175], v[212:215], v[110:113]
	v_mfma_f32_16x16x32_bf16 v[106:109], v[180:183], v[212:215], v[106:109]
	v_mfma_f32_16x16x32_bf16 v[94:97], v[172:175], v[220:223], v[94:97]
	v_mfma_f32_16x16x32_bf16 v[90:93], v[180:183], v[220:223], v[90:93]
	v_mfma_f32_16x16x32_bf16 v[78:81], v[172:175], v[228:231], v[78:81]
	v_mfma_f32_16x16x32_bf16 v[74:77], v[180:183], v[228:231], v[74:77]
	s_setprio 0
	s_setprio 1
	v_mfma_f32_16x16x32_bf16 v[118:121], v[184:187], v[200:203], 0
	v_mfma_f32_16x16x32_bf16 v[114:117], v[192:195], v[200:203], 0
	v_mfma_f32_16x16x32_bf16 v[102:105], v[184:187], v[208:211], 0
	v_mfma_f32_16x16x32_bf16 v[98:101], v[192:195], v[208:211], 0
	v_mfma_f32_16x16x32_bf16 v[86:89], v[184:187], v[216:219], 0
	v_mfma_f32_16x16x32_bf16 v[82:85], v[192:195], v[216:219], 0
	v_mfma_f32_16x16x32_bf16 v[70:73], v[184:187], v[224:227], 0
	v_mfma_f32_16x16x32_bf16 v[66:69], v[192:195], v[224:227], 0
	v_mfma_f32_16x16x32_bf16 v[118:121], v[188:191], v[204:207], v[118:121]
	v_mfma_f32_16x16x32_bf16 v[114:117], v[196:199], v[204:207], v[114:117]
	v_mfma_f32_16x16x32_bf16 v[102:105], v[188:191], v[212:215], v[102:105]
	v_mfma_f32_16x16x32_bf16 v[98:101], v[196:199], v[212:215], v[98:101]
	v_mfma_f32_16x16x32_bf16 v[86:89], v[188:191], v[220:223], v[86:89]
	v_mfma_f32_16x16x32_bf16 v[82:85], v[196:199], v[220:223], v[82:85]
	v_mfma_f32_16x16x32_bf16 v[70:73], v[188:191], v[228:231], v[70:73]
	v_mfma_f32_16x16x32_bf16 v[66:69], v[196:199], v[228:231], v[66:69]
	s_setprio 0
	s_barrier
	s_mov_b32 m0, s44
	v_lshl_add_u64 v[236:237], v[234:235], 0, v[134:135]
	ds_read_b128 v[200:203], v162 offset:16384
	ds_read_b128 v[204:207], v162 offset:17408
	ds_read_b128 v[208:211], v162 offset:18432
	ds_read_b128 v[212:215], v162 offset:19456
	ds_read_b128 v[216:219], v162 offset:20480
	ds_read_b128 v[220:223], v162 offset:21504
	ds_read_b128 v[224:227], v162 offset:22528
	ds_read_b128 v[228:231], v162 offset:23552
	global_load_lds_dwordx4 v[236:237], off
	v_lshl_add_u64 v[238:239], v[234:235], 0, v[136:137]
	s_mov_b32 m0, s45
	v_lshl_add_u64 v[240:241], v[234:235], 0, s[10:11]
	global_load_lds_dwordx4 v[238:239], off
	v_lshl_add_u64 v[242:243], v[240:241], 0, v[134:135]
	s_mov_b32 m0, s46
	v_lshl_add_u64 v[240:241], v[240:241], 0, v[136:137]
	global_load_lds_dwordx4 v[242:243], off
	s_mov_b32 m0, s47
	v_lshl_add_u64 v[242:243], v[232:233], 0, v[136:137]
	global_load_lds_dwordx4 v[240:241], off
	v_lshl_add_u64 v[240:241], v[232:233], 0, v[134:135]
	s_mov_b32 m0, s0
	s_nop 0
	global_load_lds_dwordx4 v[240:241], off
	s_mov_b32 m0, s1
	s_nop 0
	global_load_lds_dwordx4 v[242:243], off
	s_waitcnt vmcnt(8)
	s_waitcnt lgkmcnt(0)
	s_barrier
	s_setprio 1
	s_waitcnt lgkmcnt(0)
	v_mfma_f32_16x16x32_bf16 v[62:65], v[168:171], v[200:203], 0
	v_mfma_f32_16x16x32_bf16 v[58:61], v[176:179], v[200:203], 0
	v_mfma_f32_16x16x32_bf16 v[46:49], v[168:171], v[208:211], 0
	v_mfma_f32_16x16x32_bf16 v[42:45], v[176:179], v[208:211], 0
	v_mfma_f32_16x16x32_bf16 v[30:33], v[168:171], v[216:219], 0
	v_mfma_f32_16x16x32_bf16 v[26:29], v[176:179], v[216:219], 0
	v_mfma_f32_16x16x32_bf16 v[14:17], v[168:171], v[224:227], 0
	v_mfma_f32_16x16x32_bf16 v[10:13], v[176:179], v[224:227], 0
	v_mfma_f32_16x16x32_bf16 v[62:65], v[172:175], v[204:207], v[62:65]
	v_mfma_f32_16x16x32_bf16 v[58:61], v[180:183], v[204:207], v[58:61]
	v_mfma_f32_16x16x32_bf16 v[46:49], v[172:175], v[212:215], v[46:49]
	v_mfma_f32_16x16x32_bf16 v[42:45], v[180:183], v[212:215], v[42:45]
	v_mfma_f32_16x16x32_bf16 v[30:33], v[172:175], v[220:223], v[30:33]
	v_mfma_f32_16x16x32_bf16 v[26:29], v[180:183], v[220:223], v[26:29]
	v_mfma_f32_16x16x32_bf16 v[14:17], v[172:175], v[228:231], v[14:17]
	v_mfma_f32_16x16x32_bf16 v[10:13], v[180:183], v[228:231], v[10:13]
	s_setprio 0
	s_setprio 1
	v_mfma_f32_16x16x32_bf16 v[54:57], v[184:187], v[200:203], 0
	v_mfma_f32_16x16x32_bf16 v[50:53], v[192:195], v[200:203], 0
	v_mfma_f32_16x16x32_bf16 v[38:41], v[184:187], v[208:211], 0
	v_mfma_f32_16x16x32_bf16 v[34:37], v[192:195], v[208:211], 0
	v_mfma_f32_16x16x32_bf16 v[22:25], v[184:187], v[216:219], 0
	v_mfma_f32_16x16x32_bf16 v[18:21], v[192:195], v[216:219], 0
	v_mfma_f32_16x16x32_bf16 v[6:9], v[184:187], v[224:227], 0
	v_mfma_f32_16x16x32_bf16 v[2:5], v[192:195], v[224:227], 0
	v_mfma_f32_16x16x32_bf16 v[54:57], v[188:191], v[204:207], v[54:57]
	v_mfma_f32_16x16x32_bf16 v[50:53], v[196:199], v[204:207], v[50:53]
	v_mfma_f32_16x16x32_bf16 v[38:41], v[188:191], v[212:215], v[38:41]
	v_mfma_f32_16x16x32_bf16 v[34:37], v[196:199], v[212:215], v[34:37]
	v_mfma_f32_16x16x32_bf16 v[22:25], v[188:191], v[220:223], v[22:25]
	v_mfma_f32_16x16x32_bf16 v[18:21], v[196:199], v[220:223], v[18:21]
	v_mfma_f32_16x16x32_bf16 v[6:9], v[188:191], v[228:231], v[6:9]
	v_mfma_f32_16x16x32_bf16 v[2:5], v[196:199], v[228:231], v[2:5]
	s_setprio 0
	s_barrier
	ds_read_b128 v[168:171], v163
	ds_read_b128 v[172:175], v163 offset:1024
	ds_read_b128 v[176:179], v163 offset:2048
	ds_read_b128 v[180:183], v163 offset:3072
	ds_read_b128 v[184:187], v164
	ds_read_b128 v[188:191], v164 offset:1024
	ds_read_b128 v[192:195], v164 offset:2048
	ds_read_b128 v[196:199], v164 offset:3072
	v_lshl_add_u64 v[232:233], v[232:233], 0, s[10:11]
	s_mov_b32 m0, s2
	v_lshl_add_u64 v[244:245], v[232:233], 0, v[134:135]
	ds_read_b128 v[200:203], v162 offset:32768
	ds_read_b128 v[204:207], v162 offset:33792
	ds_read_b128 v[208:211], v162 offset:34816
	ds_read_b128 v[212:215], v162 offset:35840
	ds_read_b128 v[216:219], v162 offset:36864
	ds_read_b128 v[220:223], v162 offset:37888
	ds_read_b128 v[224:227], v162 offset:38912
	ds_read_b128 v[228:231], v162 offset:39936
	global_load_lds_dwordx4 v[244:245], off
	v_lshl_add_u64 v[232:233], v[232:233], 0, v[136:137]
	s_mov_b32 m0, s3
	s_nop 0
	global_load_lds_dwordx4 v[232:233], off
	s_waitcnt vmcnt(8)
	s_waitcnt lgkmcnt(0)
	s_barrier
	s_setprio 1
	s_waitcnt lgkmcnt(0)
	v_mfma_f32_16x16x32_bf16 v[126:129], v[168:171], v[200:203], v[126:129]
	v_mfma_f32_16x16x32_bf16 v[122:125], v[176:179], v[200:203], v[122:125]
	v_mfma_f32_16x16x32_bf16 v[110:113], v[168:171], v[208:211], v[110:113]
	v_mfma_f32_16x16x32_bf16 v[106:109], v[176:179], v[208:211], v[106:109]
	v_mfma_f32_16x16x32_bf16 v[94:97], v[168:171], v[216:219], v[94:97]
	v_mfma_f32_16x16x32_bf16 v[90:93], v[176:179], v[216:219], v[90:93]
	v_mfma_f32_16x16x32_bf16 v[78:81], v[168:171], v[224:227], v[78:81]
	v_mfma_f32_16x16x32_bf16 v[74:77], v[176:179], v[224:227], v[74:77]
	v_mfma_f32_16x16x32_bf16 v[126:129], v[172:175], v[204:207], v[126:129]
	v_mfma_f32_16x16x32_bf16 v[122:125], v[180:183], v[204:207], v[122:125]
	v_mfma_f32_16x16x32_bf16 v[110:113], v[172:175], v[212:215], v[110:113]
	v_mfma_f32_16x16x32_bf16 v[106:109], v[180:183], v[212:215], v[106:109]
	v_mfma_f32_16x16x32_bf16 v[94:97], v[172:175], v[220:223], v[94:97]
	v_mfma_f32_16x16x32_bf16 v[90:93], v[180:183], v[220:223], v[90:93]
	v_mfma_f32_16x16x32_bf16 v[78:81], v[172:175], v[228:231], v[78:81]
	v_mfma_f32_16x16x32_bf16 v[74:77], v[180:183], v[228:231], v[74:77]
	s_setprio 0
	s_setprio 1
	v_mfma_f32_16x16x32_bf16 v[118:121], v[184:187], v[200:203], v[118:121]
	v_mfma_f32_16x16x32_bf16 v[114:117], v[192:195], v[200:203], v[114:117]
	v_mfma_f32_16x16x32_bf16 v[102:105], v[184:187], v[208:211], v[102:105]
	v_mfma_f32_16x16x32_bf16 v[98:101], v[192:195], v[208:211], v[98:101]
	v_mfma_f32_16x16x32_bf16 v[86:89], v[184:187], v[216:219], v[86:89]
	v_mfma_f32_16x16x32_bf16 v[82:85], v[192:195], v[216:219], v[82:85]
	v_mfma_f32_16x16x32_bf16 v[70:73], v[184:187], v[224:227], v[70:73]
	v_mfma_f32_16x16x32_bf16 v[66:69], v[192:195], v[224:227], v[66:69]
	v_mfma_f32_16x16x32_bf16 v[118:121], v[188:191], v[204:207], v[118:121]
	v_mfma_f32_16x16x32_bf16 v[114:117], v[196:199], v[204:207], v[114:117]
	v_mfma_f32_16x16x32_bf16 v[102:105], v[188:191], v[212:215], v[102:105]
	v_mfma_f32_16x16x32_bf16 v[98:101], v[196:199], v[212:215], v[98:101]
	v_mfma_f32_16x16x32_bf16 v[86:89], v[188:191], v[220:223], v[86:89]
	v_mfma_f32_16x16x32_bf16 v[82:85], v[196:199], v[220:223], v[82:85]
	v_mfma_f32_16x16x32_bf16 v[70:73], v[188:191], v[228:231], v[70:73]
	v_mfma_f32_16x16x32_bf16 v[66:69], v[196:199], v[228:231], v[66:69]
	s_setprio 0
	s_barrier
	s_mov_b32 m0, s48
	v_lshl_add_u64 v[232:233], v[236:237], 0, s[14:15]
	ds_read_b128 v[200:203], v162 offset:49152
	ds_read_b128 v[204:207], v162 offset:50176
	ds_read_b128 v[208:211], v162 offset:51200
	ds_read_b128 v[212:215], v162 offset:52224
	ds_read_b128 v[216:219], v162 offset:53248
	ds_read_b128 v[220:223], v162 offset:54272
	ds_read_b128 v[224:227], v162 offset:55296
	ds_read_b128 v[228:231], v162 offset:56320
	global_load_lds_dwordx4 v[232:233], off
	v_lshl_add_u64 v[232:233], v[238:239], 0, s[14:15]
	s_mov_b32 m0, s51
	s_nop 0
	global_load_lds_dwordx4 v[232:233], off
	v_lshl_add_u64 v[232:233], v[234:235], 0, s[16:17]
	v_lshl_add_u64 v[234:235], v[232:233], 0, v[134:135]
	s_mov_b32 m0, s52
	v_lshl_add_u64 v[232:233], v[232:233], 0, v[136:137]
	global_load_lds_dwordx4 v[234:235], off
	s_add_i32 m0, s52, 0x2000
	s_nop 0
	global_load_lds_dwordx4 v[232:233], off
	v_lshl_add_u64 v[232:233], v[240:241], 0, s[14:15]
	s_mov_b32 m0, s34
	s_nop 0
	global_load_lds_dwordx4 v[232:233], off
	v_lshl_add_u64 v[232:233], v[242:243], 0, s[14:15]
	s_mov_b32 m0, s35
	s_nop 0
	global_load_lds_dwordx4 v[232:233], off
	s_waitcnt vmcnt(8)
	s_waitcnt lgkmcnt(0)
	s_barrier
	s_setprio 1
	s_waitcnt lgkmcnt(0)
	v_mfma_f32_16x16x32_bf16 v[62:65], v[168:171], v[200:203], v[62:65]
	v_mfma_f32_16x16x32_bf16 v[58:61], v[176:179], v[200:203], v[58:61]
	v_mfma_f32_16x16x32_bf16 v[46:49], v[168:171], v[208:211], v[46:49]
	v_mfma_f32_16x16x32_bf16 v[42:45], v[176:179], v[208:211], v[42:45]
	v_mfma_f32_16x16x32_bf16 v[30:33], v[168:171], v[216:219], v[30:33]
	v_mfma_f32_16x16x32_bf16 v[26:29], v[176:179], v[216:219], v[26:29]
	v_mfma_f32_16x16x32_bf16 v[14:17], v[168:171], v[224:227], v[14:17]
	v_mfma_f32_16x16x32_bf16 v[10:13], v[176:179], v[224:227], v[10:13]
	v_mfma_f32_16x16x32_bf16 v[62:65], v[172:175], v[204:207], v[62:65]
	v_mfma_f32_16x16x32_bf16 v[58:61], v[180:183], v[204:207], v[58:61]
	v_mfma_f32_16x16x32_bf16 v[46:49], v[172:175], v[212:215], v[46:49]
	v_mfma_f32_16x16x32_bf16 v[42:45], v[180:183], v[212:215], v[42:45]
	v_mfma_f32_16x16x32_bf16 v[30:33], v[172:175], v[220:223], v[30:33]
	v_mfma_f32_16x16x32_bf16 v[26:29], v[180:183], v[220:223], v[26:29]
	v_mfma_f32_16x16x32_bf16 v[14:17], v[172:175], v[228:231], v[14:17]
	v_mfma_f32_16x16x32_bf16 v[10:13], v[180:183], v[228:231], v[10:13]
	s_setprio 0
	s_setprio 1
	v_mfma_f32_16x16x32_bf16 v[54:57], v[184:187], v[200:203], v[54:57]
	v_mfma_f32_16x16x32_bf16 v[50:53], v[192:195], v[200:203], v[50:53]
	v_mfma_f32_16x16x32_bf16 v[38:41], v[184:187], v[208:211], v[38:41]
	v_mfma_f32_16x16x32_bf16 v[34:37], v[192:195], v[208:211], v[34:37]
	v_mfma_f32_16x16x32_bf16 v[22:25], v[184:187], v[216:219], v[22:25]
	v_mfma_f32_16x16x32_bf16 v[18:21], v[192:195], v[216:219], v[18:21]
	v_mfma_f32_16x16x32_bf16 v[6:9], v[184:187], v[224:227], v[6:9]
	v_mfma_f32_16x16x32_bf16 v[2:5], v[192:195], v[224:227], v[2:5]
	v_mfma_f32_16x16x32_bf16 v[54:57], v[188:191], v[204:207], v[54:57]
	v_mfma_f32_16x16x32_bf16 v[50:53], v[196:199], v[204:207], v[50:53]
	v_mfma_f32_16x16x32_bf16 v[38:41], v[188:191], v[212:215], v[38:41]
	v_mfma_f32_16x16x32_bf16 v[34:37], v[196:199], v[212:215], v[34:37]
	v_mfma_f32_16x16x32_bf16 v[22:25], v[188:191], v[220:223], v[22:25]
	v_mfma_f32_16x16x32_bf16 v[18:21], v[196:199], v[220:223], v[18:21]
	v_mfma_f32_16x16x32_bf16 v[6:9], v[188:191], v[228:231], v[6:9]
	v_mfma_f32_16x16x32_bf16 v[2:5], v[196:199], v[228:231], v[2:5]
	s_setprio 0
	s_barrier
	s_add_i32 s7, s7, 2
	v_lshl_add_u64 v[154:155], v[154:155], 0, s[20:21]
	s_cmp_gt_u32 s7, 13
	v_lshl_add_u64 v[156:157], v[156:157], 0, s[20:21]
	s_cbranch_scc0 .LBB0_213
	s_branch .Lpeel_exit_1

.Lpeel_exit_1:
	s_and_b64 vcc, exec, s[18:19]
	s_cbranch_vccz .LBB0_216
	s_barrier

.LBB0_675:
	s_ashr_i32 s45, s44, 31
	s_lshl_b64 s[8:9], s[44:45], 19
	s_ashr_i32 s43, s42, 31
	v_lshl_add_u64 v[162:163], v[146:147], 0, s[8:9]
	s_lshl_b64 s[8:9], s[42:43], 19
	v_lshl_add_u64 v[164:165], v[140:141], 0, s[8:9]
	v_cndmask_b32_e64 v132, v2, v164, s[4:5]
	v_lshl_add_u64 v[136:137], v[2:3], 0, s[36:37]
	v_mov_b32_e32 v2, 0
	v_cndmask_b32_e64 v1, v5, v163, s[4:5]
	v_cndmask_b32_e64 v130, v4, v162, s[4:5]
	v_cndmask_b32_e64 v131, v3, v165, s[4:5]
	v_lshl_add_u64 v[134:135], v[4:5], 0, s[26:27]
	s_mov_b32 s3, -2
	ds_read_b128 v[168:171], v180
	ds_read_b128 v[172:175], v180 offset:1024
	ds_read_b128 v[184:187], v180 offset:2048
	ds_read_b128 v[188:191], v180 offset:3072
	ds_read_b128 v[192:195], v181
	ds_read_b128 v[200:203], v181 offset:1024
	ds_read_b128 v[204:207], v181 offset:2048
	ds_read_b128 v[208:211], v181 offset:3072
	s_cmp_eq_u32 s3, 12
	v_lshl_add_u64 v[196:197], v[134:135], 0, s[38:39]
	s_cselect_b64 vcc, -1, 0
	v_cndmask_b32_e32 v197, v197, v1, vcc
	v_cndmask_b32_e32 v196, v196, v130, vcc
	v_cndmask_b32_e32 v245, v137, v131, vcc
	v_cndmask_b32_e32 v244, v136, v132, vcc
	s_mov_b32 m0, s56
	v_lshl_add_u64 v[246:247], v[134:135], 0, v[156:157]
	ds_read_b128 v[212:215], v178
	ds_read_b128 v[216:219], v178 offset:1024
	ds_read_b128 v[220:223], v178 offset:2048
	ds_read_b128 v[224:227], v178 offset:3072
	ds_read_b128 v[228:231], v178 offset:4096
	ds_read_b128 v[232:235], v178 offset:5120
	ds_read_b128 v[236:239], v178 offset:6144
	ds_read_b128 v[240:243], v178 offset:7168
	global_load_lds_dwordx4 v[246:247], off
	v_lshl_add_u64 v[246:247], v[134:135], 0, v[158:159]
	s_mov_b32 m0, s57
	s_nop 0
	global_load_lds_dwordx4 v[246:247], off
	s_waitcnt vmcnt(8)
	s_waitcnt lgkmcnt(0)
	s_barrier
	s_setprio 1
	s_waitcnt lgkmcnt(0)
	v_mfma_f32_16x16x32_bf16 v[126:129], v[168:171], v[212:215], 0
	v_mfma_f32_16x16x32_bf16 v[122:125], v[184:187], v[212:215], 0
	v_mfma_f32_16x16x32_bf16 v[110:113], v[168:171], v[220:223], 0
	v_mfma_f32_16x16x32_bf16 v[106:109], v[184:187], v[220:223], 0
	v_mfma_f32_16x16x32_bf16 v[94:97], v[168:171], v[228:231], 0
	v_mfma_f32_16x16x32_bf16 v[90:93], v[184:187], v[228:231], 0
	v_mfma_f32_16x16x32_bf16 v[78:81], v[168:171], v[236:239], 0
	v_mfma_f32_16x16x32_bf16 v[74:77], v[184:187], v[236:239], 0
	v_mfma_f32_16x16x32_bf16 v[126:129], v[172:175], v[216:219], v[126:129]
	v_mfma_f32_16x16x32_bf16 v[122:125], v[188:191], v[216:219], v[122:125]
	v_mfma_f32_16x16x32_bf16 v[110:113], v[172:175], v[224:227], v[110:113]
	v_mfma_f32_16x16x32_bf16 v[106:109], v[188:191], v[224:227], v[106:109]
	v_mfma_f32_16x16x32_bf16 v[94:97], v[172:175], v[232:235], v[94:97]
	v_mfma_f32_16x16x32_bf16 v[90:93], v[188:191], v[232:235], v[90:93]
	v_mfma_f32_16x16x32_bf16 v[78:81], v[172:175], v[240:243], v[78:81]
	v_mfma_f32_16x16x32_bf16 v[74:77], v[188:191], v[240:243], v[74:77]
	s_setprio 0
	s_setprio 1
	v_mfma_f32_16x16x32_bf16 v[118:121], v[192:195], v[212:215], 0
	v_mfma_f32_16x16x32_bf16 v[114:117], v[204:207], v[212:215], 0
	v_mfma_f32_16x16x32_bf16 v[102:105], v[192:195], v[220:223], 0
	v_mfma_f32_16x16x32_bf16 v[98:101], v[204:207], v[220:223], 0
	v_mfma_f32_16x16x32_bf16 v[86:89], v[192:195], v[228:231], 0
	v_mfma_f32_16x16x32_bf16 v[82:85], v[204:207], v[228:231], 0
	v_mfma_f32_16x16x32_bf16 v[70:73], v[192:195], v[236:239], 0
	v_mfma_f32_16x16x32_bf16 v[66:69], v[204:207], v[236:239], 0
	v_mfma_f32_16x16x32_bf16 v[118:121], v[200:203], v[216:219], v[118:121]
	v_mfma_f32_16x16x32_bf16 v[114:117], v[208:211], v[216:219], v[114:117]
	v_mfma_f32_16x16x32_bf16 v[102:105], v[200:203], v[224:227], v[102:105]
	v_mfma_f32_16x16x32_bf16 v[98:101], v[208:211], v[224:227], v[98:101]
	v_mfma_f32_16x16x32_bf16 v[86:89], v[200:203], v[232:235], v[86:89]
	v_mfma_f32_16x16x32_bf16 v[82:85], v[208:211], v[232:235], v[82:85]
	v_mfma_f32_16x16x32_bf16 v[70:73], v[200:203], v[240:243], v[70:73]
	v_mfma_f32_16x16x32_bf16 v[66:69], v[208:211], v[240:243], v[66:69]
	s_setprio 0
	s_barrier
	s_mov_b32 m0, s58
	v_lshl_add_u64 v[246:247], v[244:245], 0, v[142:143]
	ds_read_b128 v[212:215], v178 offset:16384
	ds_read_b128 v[216:219], v178 offset:17408
	ds_read_b128 v[220:223], v178 offset:18432
	ds_read_b128 v[224:227], v178 offset:19456
	ds_read_b128 v[228:231], v178 offset:20480
	ds_read_b128 v[232:235], v178 offset:21504
	ds_read_b128 v[236:239], v178 offset:22528
	ds_read_b128 v[240:243], v178 offset:23552
	global_load_lds_dwordx4 v[246:247], off
	v_lshl_add_u64 v[248:249], v[244:245], 0, v[144:145]
	s_add_i32 m0, s58, 0x2000
	v_lshl_add_u64 v[250:251], v[244:245], 0, s[16:17]
	s_add_i32 s7, s55, s0
	global_load_lds_dwordx4 v[248:249], off
	v_lshl_add_u64 v[252:253], v[250:251], 0, v[142:143]
	s_mov_b32 m0, s7
	v_lshl_add_u64 v[250:251], v[250:251], 0, v[144:145]
	global_load_lds_dwordx4 v[252:253], off
	s_add_i32 m0, s7, 0x2000
	v_lshl_add_u64 v[252:253], v[196:197], 0, v[144:145]
	global_load_lds_dwordx4 v[250:251], off
	v_lshl_add_u64 v[250:251], v[196:197], 0, v[142:143]
	s_mov_b32 m0, s1
	s_nop 0
	global_load_lds_dwordx4 v[250:251], off
	s_mov_b32 m0, s2
	s_nop 0
	global_load_lds_dwordx4 v[252:253], off
	s_waitcnt vmcnt(8)
	s_waitcnt lgkmcnt(0)
	s_barrier
	s_setprio 1
	s_waitcnt lgkmcnt(0)
	v_mfma_f32_16x16x32_bf16 v[62:65], v[168:171], v[212:215], 0
	v_mfma_f32_16x16x32_bf16 v[58:61], v[184:187], v[212:215], 0
	v_mfma_f32_16x16x32_bf16 v[46:49], v[168:171], v[220:223], 0
	v_mfma_f32_16x16x32_bf16 v[42:45], v[184:187], v[220:223], 0
	v_mfma_f32_16x16x32_bf16 v[30:33], v[168:171], v[228:231], 0
	v_mfma_f32_16x16x32_bf16 v[26:29], v[184:187], v[228:231], 0
	v_mfma_f32_16x16x32_bf16 v[14:17], v[168:171], v[236:239], 0
	v_mfma_f32_16x16x32_bf16 v[10:13], v[184:187], v[236:239], 0
	v_mfma_f32_16x16x32_bf16 v[62:65], v[172:175], v[216:219], v[62:65]
	v_mfma_f32_16x16x32_bf16 v[58:61], v[188:191], v[216:219], v[58:61]
	v_mfma_f32_16x16x32_bf16 v[46:49], v[172:175], v[224:227], v[46:49]
	v_mfma_f32_16x16x32_bf16 v[42:45], v[188:191], v[224:227], v[42:45]
	v_mfma_f32_16x16x32_bf16 v[30:33], v[172:175], v[232:235], v[30:33]
	v_mfma_f32_16x16x32_bf16 v[26:29], v[188:191], v[232:235], v[26:29]
	v_mfma_f32_16x16x32_bf16 v[14:17], v[172:175], v[240:243], v[14:17]
	v_mfma_f32_16x16x32_bf16 v[10:13], v[188:191], v[240:243], v[10:13]
	s_setprio 0
	s_setprio 1
	v_mfma_f32_16x16x32_bf16 v[54:57], v[192:195], v[212:215], 0
	v_mfma_f32_16x16x32_bf16 v[50:53], v[204:207], v[212:215], 0
	v_mfma_f32_16x16x32_bf16 v[38:41], v[192:195], v[220:223], 0
	v_mfma_f32_16x16x32_bf16 v[34:37], v[204:207], v[220:223], 0
	v_mfma_f32_16x16x32_bf16 v[22:25], v[192:195], v[228:231], 0
	v_mfma_f32_16x16x32_bf16 v[18:21], v[204:207], v[228:231], 0
	v_mfma_f32_16x16x32_bf16 v[6:9], v[192:195], v[236:239], 0
	v_mfma_f32_16x16x32_bf16 v[2:5], v[204:207], v[236:239], 0
	v_mfma_f32_16x16x32_bf16 v[54:57], v[200:203], v[216:219], v[54:57]
	v_mfma_f32_16x16x32_bf16 v[50:53], v[208:211], v[216:219], v[50:53]
	v_mfma_f32_16x16x32_bf16 v[38:41], v[200:203], v[224:227], v[38:41]
	v_mfma_f32_16x16x32_bf16 v[34:37], v[208:211], v[224:227], v[34:37]
	v_mfma_f32_16x16x32_bf16 v[22:25], v[200:203], v[232:235], v[22:25]
	v_mfma_f32_16x16x32_bf16 v[18:21], v[208:211], v[232:235], v[18:21]
	v_mfma_f32_16x16x32_bf16 v[6:9], v[200:203], v[240:243], v[6:9]
	v_mfma_f32_16x16x32_bf16 v[2:5], v[208:211], v[240:243], v[2:5]
	s_setprio 0
	s_barrier
	s_add_i32 s7, 0, 0x18000
	v_add_u32_e32 v133, s7, v177
	s_add_i32 s8, 0, 0x1c000
	ds_read_b128 v[168:171], v133
	ds_read_b128 v[172:175], v133 offset:1024
	ds_read_b128 v[184:187], v133 offset:2048
	ds_read_b128 v[188:191], v133 offset:3072
	v_add_u32_e32 v133, s8, v177
	ds_read_b128 v[192:195], v133
	ds_read_b128 v[200:203], v133 offset:1024
	ds_read_b128 v[204:207], v133 offset:2048
	ds_read_b128 v[208:211], v133 offset:3072
	v_lshl_add_u64 v[196:197], v[196:197], 0, s[16:17]
	s_mov_b32 m0, s33
	v_lshl_add_u64 v[198:199], v[196:197], 0, v[142:143]
	ds_read_b128 v[212:215], v178 offset:32768
	ds_read_b128 v[216:219], v178 offset:33792
	ds_read_b128 v[220:223], v178 offset:34816
	ds_read_b128 v[224:227], v178 offset:35840
	ds_read_b128 v[228:231], v178 offset:36864
	ds_read_b128 v[232:235], v178 offset:37888
	ds_read_b128 v[236:239], v178 offset:38912
	ds_read_b128 v[240:243], v178 offset:39936
	global_load_lds_dwordx4 v[198:199], off
	v_lshl_add_u64 v[196:197], v[196:197], 0, v[144:145]
	s_mov_b32 m0, s34
	s_nop 0
	global_load_lds_dwordx4 v[196:197], off
	s_waitcnt vmcnt(8)
	s_waitcnt lgkmcnt(0)
	s_barrier
	s_setprio 1
	s_waitcnt lgkmcnt(0)
	v_mfma_f32_16x16x32_bf16 v[126:129], v[168:171], v[212:215], v[126:129]
	v_mfma_f32_16x16x32_bf16 v[122:125], v[184:187], v[212:215], v[122:125]
	v_mfma_f32_16x16x32_bf16 v[110:113], v[168:171], v[220:223], v[110:113]
	v_mfma_f32_16x16x32_bf16 v[106:109], v[184:187], v[220:223], v[106:109]
	v_mfma_f32_16x16x32_bf16 v[94:97], v[168:171], v[228:231], v[94:97]
	v_mfma_f32_16x16x32_bf16 v[90:93], v[184:187], v[228:231], v[90:93]
	v_mfma_f32_16x16x32_bf16 v[78:81], v[168:171], v[236:239], v[78:81]
	v_mfma_f32_16x16x32_bf16 v[74:77], v[184:187], v[236:239], v[74:77]
	v_mfma_f32_16x16x32_bf16 v[126:129], v[172:175], v[216:219], v[126:129]
	v_mfma_f32_16x16x32_bf16 v[122:125], v[188:191], v[216:219], v[122:125]
	v_mfma_f32_16x16x32_bf16 v[110:113], v[172:175], v[224:227], v[110:113]
	v_mfma_f32_16x16x32_bf16 v[106:109], v[188:191], v[224:227], v[106:109]
	v_mfma_f32_16x16x32_bf16 v[94:97], v[172:175], v[232:235], v[94:97]
	v_mfma_f32_16x16x32_bf16 v[90:93], v[188:191], v[232:235], v[90:93]
	v_mfma_f32_16x16x32_bf16 v[78:81], v[172:175], v[240:243], v[78:81]
	v_mfma_f32_16x16x32_bf16 v[74:77], v[188:191], v[240:243], v[74:77]
	s_setprio 0
	s_setprio 1
	v_mfma_f32_16x16x32_bf16 v[118:121], v[192:195], v[212:215], v[118:121]
	v_mfma_f32_16x16x32_bf16 v[114:117], v[204:207], v[212:215], v[114:117]
	v_mfma_f32_16x16x32_bf16 v[102:105], v[192:195], v[220:223], v[102:105]
	v_mfma_f32_16x16x32_bf16 v[98:101], v[204:207], v[220:223], v[98:101]
	v_mfma_f32_16x16x32_bf16 v[86:89], v[192:195], v[228:231], v[86:89]
	v_mfma_f32_16x16x32_bf16 v[82:85], v[204:207], v[228:231], v[82:85]
	v_mfma_f32_16x16x32_bf16 v[70:73], v[192:195], v[236:239], v[70:73]
	v_mfma_f32_16x16x32_bf16 v[66:69], v[204:207], v[236:239], v[66:69]
	v_mfma_f32_16x16x32_bf16 v[118:121], v[200:203], v[216:219], v[118:121]
	v_mfma_f32_16x16x32_bf16 v[114:117], v[208:211], v[216:219], v[114:117]
	v_mfma_f32_16x16x32_bf16 v[102:105], v[200:203], v[224:227], v[102:105]
	v_mfma_f32_16x16x32_bf16 v[98:101], v[208:211], v[224:227], v[98:101]
	v_mfma_f32_16x16x32_bf16 v[86:89], v[200:203], v[232:235], v[86:89]
	v_mfma_f32_16x16x32_bf16 v[82:85], v[208:211], v[232:235], v[82:85]
	v_mfma_f32_16x16x32_bf16 v[70:73], v[200:203], v[240:243], v[70:73]
	v_mfma_f32_16x16x32_bf16 v[66:69], v[208:211], v[240:243], v[66:69]
	s_setprio 0
	s_barrier
	s_add_i32 s7, s7, s0
	v_lshl_add_u64 v[196:197], v[246:247], 0, s[24:25]
	s_mov_b32 m0, s7
	ds_read_b128 v[212:215], v178 offset:49152
	ds_read_b128 v[216:219], v178 offset:50176
	ds_read_b128 v[220:223], v178 offset:51200
	ds_read_b128 v[224:227], v178 offset:52224
	ds_read_b128 v[228:231], v178 offset:53248
	ds_read_b128 v[232:235], v178 offset:54272
	ds_read_b128 v[236:239], v178 offset:55296
	ds_read_b128 v[240:243], v178 offset:56320
	global_load_lds_dwordx4 v[196:197], off
	v_lshl_add_u64 v[196:197], v[248:249], 0, s[24:25]
	s_add_i32 m0, s7, 0x2000
	s_add_i32 s7, s8, s0
	global_load_lds_dwordx4 v[196:197], off
	v_lshl_add_u64 v[196:197], v[244:245], 0, s[26:27]
	v_lshl_add_u64 v[198:199], v[196:197], 0, v[142:143]
	s_mov_b32 m0, s7
	v_lshl_add_u64 v[196:197], v[196:197], 0, v[144:145]
	global_load_lds_dwordx4 v[198:199], off
	s_add_i32 m0, s7, 0x2000
	s_nop 0
	global_load_lds_dwordx4 v[196:197], off
	v_lshl_add_u64 v[196:197], v[250:251], 0, s[24:25]
	s_mov_b32 m0, s49
	s_nop 0
	global_load_lds_dwordx4 v[196:197], off
	v_lshl_add_u64 v[196:197], v[252:253], 0, s[24:25]
	s_mov_b32 m0, s50
	s_nop 0
	global_load_lds_dwordx4 v[196:197], off
	s_waitcnt vmcnt(8)
	s_waitcnt lgkmcnt(0)
	s_barrier
	s_setprio 1
	s_waitcnt lgkmcnt(0)
	v_mfma_f32_16x16x32_bf16 v[62:65], v[168:171], v[212:215], v[62:65]
	v_mfma_f32_16x16x32_bf16 v[58:61], v[184:187], v[212:215], v[58:61]
	v_mfma_f32_16x16x32_bf16 v[46:49], v[168:171], v[220:223], v[46:49]
	v_mfma_f32_16x16x32_bf16 v[42:45], v[184:187], v[220:223], v[42:45]
	v_mfma_f32_16x16x32_bf16 v[30:33], v[168:171], v[228:231], v[30:33]
	v_mfma_f32_16x16x32_bf16 v[26:29], v[184:187], v[228:231], v[26:29]
	v_mfma_f32_16x16x32_bf16 v[14:17], v[168:171], v[236:239], v[14:17]
	v_mfma_f32_16x16x32_bf16 v[10:13], v[184:187], v[236:239], v[10:13]
	v_mfma_f32_16x16x32_bf16 v[62:65], v[172:175], v[216:219], v[62:65]
	v_mfma_f32_16x16x32_bf16 v[58:61], v[188:191], v[216:219], v[58:61]
	v_mfma_f32_16x16x32_bf16 v[46:49], v[172:175], v[224:227], v[46:49]
	v_mfma_f32_16x16x32_bf16 v[42:45], v[188:191], v[224:227], v[42:45]
	v_mfma_f32_16x16x32_bf16 v[30:33], v[172:175], v[232:235], v[30:33]
	v_mfma_f32_16x16x32_bf16 v[26:29], v[188:191], v[232:235], v[26:29]
	v_mfma_f32_16x16x32_bf16 v[14:17], v[172:175], v[240:243], v[14:17]
	v_mfma_f32_16x16x32_bf16 v[10:13], v[188:191], v[240:243], v[10:13]
	s_setprio 0
	s_setprio 1
	v_mfma_f32_16x16x32_bf16 v[54:57], v[192:195], v[212:215], v[54:57]
	v_mfma_f32_16x16x32_bf16 v[50:53], v[204:207], v[212:215], v[50:53]
	v_mfma_f32_16x16x32_bf16 v[38:41], v[192:195], v[220:223], v[38:41]
	v_mfma_f32_16x16x32_bf16 v[34:37], v[204:207], v[220:223], v[34:37]
	v_mfma_f32_16x16x32_bf16 v[22:25], v[192:195], v[228:231], v[22:25]
	v_mfma_f32_16x16x32_bf16 v[18:21], v[204:207], v[228:231], v[18:21]
	v_mfma_f32_16x16x32_bf16 v[6:9], v[192:195], v[236:239], v[6:9]
	v_mfma_f32_16x16x32_bf16 v[2:5], v[204:207], v[236:239], v[2:5]
	v_mfma_f32_16x16x32_bf16 v[54:57], v[200:203], v[216:219], v[54:57]
	v_mfma_f32_16x16x32_bf16 v[50:53], v[208:211], v[216:219], v[50:53]
	v_mfma_f32_16x16x32_bf16 v[38:41], v[200:203], v[224:227], v[38:41]
	v_mfma_f32_16x16x32_bf16 v[34:37], v[208:211], v[224:227], v[34:37]
	v_mfma_f32_16x16x32_bf16 v[22:25], v[200:203], v[232:235], v[22:25]
	v_mfma_f32_16x16x32_bf16 v[18:21], v[208:211], v[232:235], v[18:21]
	v_mfma_f32_16x16x32_bf16 v[6:9], v[200:203], v[240:243], v[6:9]
	v_mfma_f32_16x16x32_bf16 v[2:5], v[208:211], v[240:243], v[2:5]
	s_setprio 0
	s_barrier
	s_add_i32 s3, s3, 2
	v_lshl_add_u64 v[134:135], v[134:135], 0, s[36:37]
	s_cmp_gt_u32 s3, 13
	v_lshl_add_u64 v[136:137], v[136:137], 0, s[36:37]
	s_cbranch_scc0 .LBB0_676
	s_branch .Lpeel_exit_2

.Lpeel_exit_2:
	s_and_b64 vcc, exec, s[28:29]
	s_cbranch_vccz .LBB0_679
	s_barrier

.LBB0_1064:
	s_ashr_i32 s47, s46, 31
	s_lshl_b64 s[12:13], s[46:47], 20
	s_ashr_i32 s49, s48, 31
	s_ashr_i32 s45, s44, 31
	v_lshl_add_u64 v[6:7], v[168:169], 0, s[12:13]
	s_lshl_b64 s[12:13], s[48:49], 7
	s_lshl_b64 s[52:53], s[44:45], 20
	v_lshl_add_u64 v[188:189], v[6:7], 0, s[12:13]
	v_lshl_add_u64 v[6:7], v[170:171], 0, s[52:53]
	v_lshl_add_u64 v[190:191], v[6:7], 0, s[12:13]
	s_waitcnt vmcnt(0)
	v_mov_b32_e32 v66, 0
	v_cndmask_b32_e64 v1, v5, v189, s[50:51]
	v_cndmask_b32_e64 v130, v4, v188, s[50:51]
	v_cndmask_b32_e64 v131, v3, v191, s[50:51]
	v_cndmask_b32_e64 v132, v2, v190, s[50:51]
	s_add_i32 s12, s9, -2
	v_lshl_add_u64 v[134:135], v[4:5], 0, s[24:25]
	v_lshl_add_u64 v[136:137], v[2:3], 0, s[38:39]
	s_mov_b32 s13, 0
	v_add_u32_e32 v133, s65, v204
	ds_read_b128 v[138:141], v207
	ds_read_b128 v[142:145], v207 offset:1024
	ds_read_b128 v[146:149], v207 offset:2048
	ds_read_b128 v[150:153], v207 offset:3072
	ds_read_b128 v[154:157], v133
	ds_read_b128 v[158:161], v133 offset:1024
	ds_read_b128 v[162:165], v133 offset:2048
	ds_read_b128 v[192:195], v133 offset:3072
	s_cmp_eq_u32 s12, s13
	v_lshl_add_u64 v[196:197], v[134:135], 0, s[40:41]
	s_cselect_b64 vcc, -1, 0
	s_add_i32 s13, s13, 2
	v_cndmask_b32_e32 v197, v197, v1, vcc
	v_cndmask_b32_e32 v196, v196, v130, vcc
	v_cndmask_b32_e32 v199, v137, v131, vcc
	v_cndmask_b32_e32 v198, v136, v132, vcc
	v_lshl_add_u64 v[240:241], v[134:135], 0, v[184:185]
	s_add_i32 m0, s1, 0xc000
	ds_read_b128 v[208:211], v205
	ds_read_b128 v[212:215], v205 offset:1024
	ds_read_b128 v[216:219], v205 offset:2048
	ds_read_b128 v[220:223], v205 offset:3072
	ds_read_b128 v[224:227], v205 offset:4096
	ds_read_b128 v[228:231], v205 offset:5120
	ds_read_b128 v[232:235], v205 offset:6144
	ds_read_b128 v[236:239], v205 offset:7168
	global_load_lds_dwordx4 v[240:241], off
	v_lshl_add_u64 v[240:241], v[134:135], 0, v[186:187]
	s_add_i32 m0, s1, 0xe000
	s_nop 0
	global_load_lds_dwordx4 v[240:241], off
	s_waitcnt vmcnt(8)
	s_waitcnt lgkmcnt(0)
	s_barrier
	s_setprio 1
	s_waitcnt lgkmcnt(0)
	v_mfma_f32_16x16x32_bf16 v[62:65], v[138:141], v[208:211], 0
	v_mfma_f32_16x16x32_bf16 v[58:61], v[146:149], v[208:211], 0
	v_mfma_f32_16x16x32_bf16 v[54:57], v[138:141], v[216:219], 0
	v_mfma_f32_16x16x32_bf16 v[50:53], v[146:149], v[216:219], 0
	v_mfma_f32_16x16x32_bf16 v[46:49], v[138:141], v[224:227], 0
	v_mfma_f32_16x16x32_bf16 v[42:45], v[146:149], v[224:227], 0
	v_mfma_f32_16x16x32_bf16 v[38:41], v[138:141], v[232:235], 0
	v_mfma_f32_16x16x32_bf16 v[34:37], v[146:149], v[232:235], 0
	v_mfma_f32_16x16x32_bf16 v[62:65], v[142:145], v[212:215], v[62:65]
	v_mfma_f32_16x16x32_bf16 v[58:61], v[150:153], v[212:215], v[58:61]
	v_mfma_f32_16x16x32_bf16 v[54:57], v[142:145], v[220:223], v[54:57]
	v_mfma_f32_16x16x32_bf16 v[50:53], v[150:153], v[220:223], v[50:53]
	v_mfma_f32_16x16x32_bf16 v[46:49], v[142:145], v[228:231], v[46:49]
	v_mfma_f32_16x16x32_bf16 v[42:45], v[150:153], v[228:231], v[42:45]
	v_mfma_f32_16x16x32_bf16 v[38:41], v[142:145], v[236:239], v[38:41]
	v_mfma_f32_16x16x32_bf16 v[34:37], v[150:153], v[236:239], v[34:37]
	s_setprio 0
	s_setprio 1
	v_mfma_f32_16x16x32_bf16 v[30:33], v[154:157], v[208:211], 0
	v_mfma_f32_16x16x32_bf16 v[26:29], v[162:165], v[208:211], 0
	v_mfma_f32_16x16x32_bf16 v[22:25], v[154:157], v[216:219], 0
	v_mfma_f32_16x16x32_bf16 v[18:21], v[162:165], v[216:219], 0
	v_mfma_f32_16x16x32_bf16 v[14:17], v[154:157], v[224:227], 0
	v_mfma_f32_16x16x32_bf16 v[10:13], v[162:165], v[224:227], 0
	v_mfma_f32_16x16x32_bf16 v[6:9], v[154:157], v[232:235], 0
	v_mfma_f32_16x16x32_bf16 v[2:5], v[162:165], v[232:235], 0
	v_mfma_f32_16x16x32_bf16 v[30:33], v[158:161], v[212:215], v[30:33]
	v_mfma_f32_16x16x32_bf16 v[26:29], v[192:195], v[212:215], v[26:29]
	v_mfma_f32_16x16x32_bf16 v[22:25], v[158:161], v[220:223], v[22:25]
	v_mfma_f32_16x16x32_bf16 v[18:21], v[192:195], v[220:223], v[18:21]
	v_mfma_f32_16x16x32_bf16 v[14:17], v[158:161], v[228:231], v[14:17]
	v_mfma_f32_16x16x32_bf16 v[10:13], v[192:195], v[228:231], v[10:13]
	v_mfma_f32_16x16x32_bf16 v[6:9], v[158:161], v[236:239], v[6:9]
	v_mfma_f32_16x16x32_bf16 v[2:5], v[192:195], v[236:239], v[2:5]
	s_setprio 0
	s_barrier
	s_add_i32 s31, s64, s0
	v_lshl_add_u64 v[240:241], v[198:199], 0, v[172:173]
	s_mov_b32 m0, s31
	ds_read_b128 v[208:211], v205 offset:16384
	ds_read_b128 v[212:215], v205 offset:17408
	ds_read_b128 v[216:219], v205 offset:18432
	ds_read_b128 v[220:223], v205 offset:19456
	ds_read_b128 v[224:227], v205 offset:20480
	ds_read_b128 v[228:231], v205 offset:21504
	ds_read_b128 v[232:235], v205 offset:22528
	ds_read_b128 v[236:239], v205 offset:23552
	global_load_lds_dwordx4 v[240:241], off
	v_lshl_add_u64 v[242:243], v[198:199], 0, v[174:175]
	s_add_i32 m0, s31, 0x2000
	v_lshl_add_u64 v[244:245], v[198:199], 0, s[18:19]
	s_add_i32 s31, s65, s0
	global_load_lds_dwordx4 v[242:243], off
	v_lshl_add_u64 v[246:247], v[244:245], 0, v[172:173]
	s_mov_b32 m0, s31
	v_lshl_add_u64 v[244:245], v[244:245], 0, v[174:175]
	global_load_lds_dwordx4 v[246:247], off
	s_add_i32 m0, s31, 0x2000
	v_lshl_add_u64 v[246:247], v[196:197], 0, v[174:175]
	global_load_lds_dwordx4 v[244:245], off
	v_lshl_add_u64 v[244:245], v[196:197], 0, v[172:173]
	s_mov_b32 m0, s1
	s_nop 0
	global_load_lds_dwordx4 v[244:245], off
	s_mov_b32 m0, s2
	s_nop 0
	global_load_lds_dwordx4 v[246:247], off
	s_waitcnt vmcnt(8)
	s_waitcnt lgkmcnt(0)
	s_barrier
	s_setprio 1
	s_waitcnt lgkmcnt(0)
	v_mfma_f32_16x16x32_bf16 v[126:129], v[138:141], v[208:211], 0
	v_mfma_f32_16x16x32_bf16 v[122:125], v[146:149], v[208:211], 0
	v_mfma_f32_16x16x32_bf16 v[118:121], v[138:141], v[216:219], 0
	v_mfma_f32_16x16x32_bf16 v[114:117], v[146:149], v[216:219], 0
	v_mfma_f32_16x16x32_bf16 v[110:113], v[138:141], v[224:227], 0
	v_mfma_f32_16x16x32_bf16 v[106:109], v[146:149], v[224:227], 0
	v_mfma_f32_16x16x32_bf16 v[102:105], v[138:141], v[232:235], 0
	v_mfma_f32_16x16x32_bf16 v[98:101], v[146:149], v[232:235], 0
	v_mfma_f32_16x16x32_bf16 v[126:129], v[142:145], v[212:215], v[126:129]
	v_mfma_f32_16x16x32_bf16 v[122:125], v[150:153], v[212:215], v[122:125]
	v_mfma_f32_16x16x32_bf16 v[118:121], v[142:145], v[220:223], v[118:121]
	v_mfma_f32_16x16x32_bf16 v[114:117], v[150:153], v[220:223], v[114:117]
	v_mfma_f32_16x16x32_bf16 v[110:113], v[142:145], v[228:231], v[110:113]
	v_mfma_f32_16x16x32_bf16 v[106:109], v[150:153], v[228:231], v[106:109]
	v_mfma_f32_16x16x32_bf16 v[102:105], v[142:145], v[236:239], v[102:105]
	v_mfma_f32_16x16x32_bf16 v[98:101], v[150:153], v[236:239], v[98:101]
	s_setprio 0
	s_setprio 1
	v_mfma_f32_16x16x32_bf16 v[94:97], v[154:157], v[208:211], 0
	v_mfma_f32_16x16x32_bf16 v[90:93], v[162:165], v[208:211], 0
	v_mfma_f32_16x16x32_bf16 v[86:89], v[154:157], v[216:219], 0
	v_mfma_f32_16x16x32_bf16 v[82:85], v[162:165], v[216:219], 0
	v_mfma_f32_16x16x32_bf16 v[78:81], v[154:157], v[224:227], 0
	v_mfma_f32_16x16x32_bf16 v[74:77], v[162:165], v[224:227], 0
	v_mfma_f32_16x16x32_bf16 v[70:73], v[154:157], v[232:235], 0
	v_mfma_f32_16x16x32_bf16 v[66:69], v[162:165], v[232:235], 0
	v_mfma_f32_16x16x32_bf16 v[94:97], v[158:161], v[212:215], v[94:97]
	v_mfma_f32_16x16x32_bf16 v[90:93], v[192:195], v[212:215], v[90:93]
	v_mfma_f32_16x16x32_bf16 v[86:89], v[158:161], v[220:223], v[86:89]
	v_mfma_f32_16x16x32_bf16 v[82:85], v[192:195], v[220:223], v[82:85]
	v_mfma_f32_16x16x32_bf16 v[78:81], v[158:161], v[228:231], v[78:81]
	v_mfma_f32_16x16x32_bf16 v[74:77], v[192:195], v[228:231], v[74:77]
	v_mfma_f32_16x16x32_bf16 v[70:73], v[158:161], v[236:239], v[70:73]
	v_mfma_f32_16x16x32_bf16 v[66:69], v[192:195], v[236:239], v[66:69]
	s_setprio 0
	s_barrier
	s_add_i32 s31, 0, 0x18000
	v_add_u32_e32 v133, s31, v204
	s_add_i32 s45, 0, 0x1c000
	ds_read_b128 v[138:141], v133
	ds_read_b128 v[142:145], v133 offset:1024
	ds_read_b128 v[146:149], v133 offset:2048
	ds_read_b128 v[150:153], v133 offset:3072
	v_add_u32_e32 v133, s45, v204
	ds_read_b128 v[154:157], v133
	ds_read_b128 v[158:161], v133 offset:1024
	ds_read_b128 v[162:165], v133 offset:2048
	ds_read_b128 v[192:195], v133 offset:3072
	v_lshl_add_u64 v[196:197], v[196:197], 0, s[18:19]
	s_mov_b32 m0, s33
	v_lshl_add_u64 v[248:249], v[196:197], 0, v[172:173]
	ds_read_b128 v[208:211], v205 offset:32768
	ds_read_b128 v[212:215], v205 offset:33792
	ds_read_b128 v[216:219], v205 offset:34816
	ds_read_b128 v[220:223], v205 offset:35840
	ds_read_b128 v[224:227], v205 offset:36864
	ds_read_b128 v[228:231], v205 offset:37888
	ds_read_b128 v[232:235], v205 offset:38912
	ds_read_b128 v[236:239], v205 offset:39936
	global_load_lds_dwordx4 v[248:249], off
	v_lshl_add_u64 v[196:197], v[196:197], 0, v[174:175]
	s_mov_b32 m0, s34
	s_nop 0
	global_load_lds_dwordx4 v[196:197], off
	s_waitcnt vmcnt(8)
	s_waitcnt lgkmcnt(0)
	s_barrier
	s_setprio 1
	s_waitcnt lgkmcnt(0)
	v_mfma_f32_16x16x32_bf16 v[62:65], v[138:141], v[208:211], v[62:65]
	v_mfma_f32_16x16x32_bf16 v[58:61], v[146:149], v[208:211], v[58:61]
	v_mfma_f32_16x16x32_bf16 v[54:57], v[138:141], v[216:219], v[54:57]
	v_mfma_f32_16x16x32_bf16 v[50:53], v[146:149], v[216:219], v[50:53]
	v_mfma_f32_16x16x32_bf16 v[46:49], v[138:141], v[224:227], v[46:49]
	v_mfma_f32_16x16x32_bf16 v[42:45], v[146:149], v[224:227], v[42:45]
	v_mfma_f32_16x16x32_bf16 v[38:41], v[138:141], v[232:235], v[38:41]
	v_mfma_f32_16x16x32_bf16 v[34:37], v[146:149], v[232:235], v[34:37]
	v_mfma_f32_16x16x32_bf16 v[62:65], v[142:145], v[212:215], v[62:65]
	v_mfma_f32_16x16x32_bf16 v[58:61], v[150:153], v[212:215], v[58:61]
	v_mfma_f32_16x16x32_bf16 v[54:57], v[142:145], v[220:223], v[54:57]
	v_mfma_f32_16x16x32_bf16 v[50:53], v[150:153], v[220:223], v[50:53]
	v_mfma_f32_16x16x32_bf16 v[46:49], v[142:145], v[228:231], v[46:49]
	v_mfma_f32_16x16x32_bf16 v[42:45], v[150:153], v[228:231], v[42:45]
	v_mfma_f32_16x16x32_bf16 v[38:41], v[142:145], v[236:239], v[38:41]
	v_mfma_f32_16x16x32_bf16 v[34:37], v[150:153], v[236:239], v[34:37]
	s_setprio 0
	s_setprio 1
	v_mfma_f32_16x16x32_bf16 v[30:33], v[154:157], v[208:211], v[30:33]
	v_mfma_f32_16x16x32_bf16 v[26:29], v[162:165], v[208:211], v[26:29]
	v_mfma_f32_16x16x32_bf16 v[22:25], v[154:157], v[216:219], v[22:25]
	v_mfma_f32_16x16x32_bf16 v[18:21], v[162:165], v[216:219], v[18:21]
	v_mfma_f32_16x16x32_bf16 v[14:17], v[154:157], v[224:227], v[14:17]
	v_mfma_f32_16x16x32_bf16 v[10:13], v[162:165], v[224:227], v[10:13]
	v_mfma_f32_16x16x32_bf16 v[6:9], v[154:157], v[232:235], v[6:9]
	v_mfma_f32_16x16x32_bf16 v[2:5], v[162:165], v[232:235], v[2:5]
	v_mfma_f32_16x16x32_bf16 v[30:33], v[158:161], v[212:215], v[30:33]
	v_mfma_f32_16x16x32_bf16 v[26:29], v[192:195], v[212:215], v[26:29]
	v_mfma_f32_16x16x32_bf16 v[22:25], v[158:161], v[220:223], v[22:25]
	v_mfma_f32_16x16x32_bf16 v[18:21], v[192:195], v[220:223], v[18:21]
	v_mfma_f32_16x16x32_bf16 v[14:17], v[158:161], v[228:231], v[14:17]
	v_mfma_f32_16x16x32_bf16 v[10:13], v[192:195], v[228:231], v[10:13]
	v_mfma_f32_16x16x32_bf16 v[6:9], v[158:161], v[236:239], v[6:9]
	v_mfma_f32_16x16x32_bf16 v[2:5], v[192:195], v[236:239], v[2:5]
	s_setprio 0
	s_barrier
	s_add_i32 s31, s31, s0
	v_lshl_add_u64 v[196:197], v[240:241], 0, s[22:23]
	s_mov_b32 m0, s31
	ds_read_b128 v[208:211], v205 offset:49152
	ds_read_b128 v[212:215], v205 offset:50176
	ds_read_b128 v[216:219], v205 offset:51200
	ds_read_b128 v[220:223], v205 offset:52224
	ds_read_b128 v[224:227], v205 offset:53248
	ds_read_b128 v[228:231], v205 offset:54272
	ds_read_b128 v[232:235], v205 offset:55296
	ds_read_b128 v[236:239], v205 offset:56320
	global_load_lds_dwordx4 v[196:197], off
	v_lshl_add_u64 v[196:197], v[242:243], 0, s[22:23]
	s_add_i32 m0, s31, 0x2000
	s_add_i32 s31, s45, s0
	global_load_lds_dwordx4 v[196:197], off
	v_lshl_add_u64 v[196:197], v[198:199], 0, s[24:25]
	v_lshl_add_u64 v[198:199], v[196:197], 0, v[172:173]
	s_mov_b32 m0, s31
	v_lshl_add_u64 v[196:197], v[196:197], 0, v[174:175]
	global_load_lds_dwordx4 v[198:199], off
	s_add_i32 m0, s31, 0x2000
	s_nop 0
	global_load_lds_dwordx4 v[196:197], off
	v_lshl_add_u64 v[196:197], v[244:245], 0, s[22:23]
	s_mov_b32 m0, s56
	s_nop 0
	global_load_lds_dwordx4 v[196:197], off
	v_lshl_add_u64 v[196:197], v[246:247], 0, s[22:23]
	s_mov_b32 m0, s57
	s_nop 0
	global_load_lds_dwordx4 v[196:197], off
	s_waitcnt vmcnt(8)
	s_waitcnt lgkmcnt(0)
	s_barrier
	s_setprio 1
	s_waitcnt lgkmcnt(0)
	v_mfma_f32_16x16x32_bf16 v[126:129], v[138:141], v[208:211], v[126:129]
	v_mfma_f32_16x16x32_bf16 v[122:125], v[146:149], v[208:211], v[122:125]
	v_mfma_f32_16x16x32_bf16 v[118:121], v[138:141], v[216:219], v[118:121]
	v_mfma_f32_16x16x32_bf16 v[114:117], v[146:149], v[216:219], v[114:117]
	v_mfma_f32_16x16x32_bf16 v[110:113], v[138:141], v[224:227], v[110:113]
	v_mfma_f32_16x16x32_bf16 v[106:109], v[146:149], v[224:227], v[106:109]
	v_mfma_f32_16x16x32_bf16 v[102:105], v[138:141], v[232:235], v[102:105]
	v_mfma_f32_16x16x32_bf16 v[98:101], v[146:149], v[232:235], v[98:101]
	v_mfma_f32_16x16x32_bf16 v[126:129], v[142:145], v[212:215], v[126:129]
	v_mfma_f32_16x16x32_bf16 v[122:125], v[150:153], v[212:215], v[122:125]
	v_mfma_f32_16x16x32_bf16 v[118:121], v[142:145], v[220:223], v[118:121]
	v_mfma_f32_16x16x32_bf16 v[114:117], v[150:153], v[220:223], v[114:117]
	v_mfma_f32_16x16x32_bf16 v[110:113], v[142:145], v[228:231], v[110:113]
	v_mfma_f32_16x16x32_bf16 v[106:109], v[150:153], v[228:231], v[106:109]
	v_mfma_f32_16x16x32_bf16 v[102:105], v[142:145], v[236:239], v[102:105]
	v_mfma_f32_16x16x32_bf16 v[98:101], v[150:153], v[236:239], v[98:101]
	s_setprio 0
	s_setprio 1
	v_mfma_f32_16x16x32_bf16 v[94:97], v[154:157], v[208:211], v[94:97]
	v_mfma_f32_16x16x32_bf16 v[90:93], v[162:165], v[208:211], v[90:93]
	v_mfma_f32_16x16x32_bf16 v[86:89], v[154:157], v[216:219], v[86:89]
	v_mfma_f32_16x16x32_bf16 v[82:85], v[162:165], v[216:219], v[82:85]
	v_mfma_f32_16x16x32_bf16 v[78:81], v[154:157], v[224:227], v[78:81]
	v_mfma_f32_16x16x32_bf16 v[74:77], v[162:165], v[224:227], v[74:77]
	v_mfma_f32_16x16x32_bf16 v[70:73], v[154:157], v[232:235], v[70:73]
	v_mfma_f32_16x16x32_bf16 v[66:69], v[162:165], v[232:235], v[66:69]
	v_mfma_f32_16x16x32_bf16 v[94:97], v[158:161], v[212:215], v[94:97]
	v_mfma_f32_16x16x32_bf16 v[90:93], v[192:195], v[212:215], v[90:93]
	v_mfma_f32_16x16x32_bf16 v[86:89], v[158:161], v[220:223], v[86:89]
	v_mfma_f32_16x16x32_bf16 v[82:85], v[192:195], v[220:223], v[82:85]
	v_mfma_f32_16x16x32_bf16 v[78:81], v[158:161], v[228:231], v[78:81]
	v_mfma_f32_16x16x32_bf16 v[74:77], v[192:195], v[228:231], v[74:77]
	v_mfma_f32_16x16x32_bf16 v[70:73], v[158:161], v[236:239], v[70:73]
	v_mfma_f32_16x16x32_bf16 v[66:69], v[192:195], v[236:239], v[66:69]
	s_setprio 0
	s_barrier
	v_lshl_add_u64 v[134:135], v[134:135], 0, s[38:39]
	s_cmp_ge_i32 s13, s9
	v_lshl_add_u64 v[136:137], v[136:137], 0, s[38:39]
	s_cbranch_scc0 .LBB0_1065
	s_branch .Lpeel_exit_3

.Lpeel_exit_3:
	s_and_b64 vcc, exec, s[26:27]
	s_cbranch_vccz .LBB0_1068
	s_barrier

.LBB0_1251:
	s_ashr_i32 s47, s46, 31
	s_lshl_b64 s[8:9], s[46:47], 19
	s_ashr_i32 s45, s44, 31
	v_lshl_add_u64 v[170:171], v[146:147], 0, s[8:9]
	s_lshl_b64 s[8:9], s[44:45], 19
	v_lshl_add_u64 v[172:173], v[148:149], 0, s[8:9]
	s_waitcnt vmcnt(0)
	v_cndmask_b32_e64 v84, v2, v172, s[4:5]
	v_lshl_add_u64 v[88:89], v[2:3], 0, s[40:41]
	v_mov_b32_e32 v2, 0
	v_cndmask_b32_e64 v1, v5, v171, s[4:5]
	v_cndmask_b32_e64 v82, v4, v170, s[4:5]
	v_cndmask_b32_e64 v83, v3, v173, s[4:5]
	v_lshl_add_u64 v[86:87], v[4:5], 0, s[28:29]
	s_mov_b32 s7, -2
	ds_read_b128 v[94:97], v181
	ds_read_b128 v[98:101], v181 offset:1024
	ds_read_b128 v[174:177], v181 offset:2048
	ds_read_b128 v[186:189], v181 offset:3072
	ds_read_b128 v[190:193], v183
	ds_read_b128 v[194:197], v183 offset:1024
	ds_read_b128 v[200:203], v183 offset:2048
	ds_read_b128 v[204:207], v183 offset:3072
	s_cmp_eq_u32 s7, 12
	v_lshl_add_u64 v[198:199], v[86:87], 0, s[42:43]
	s_cselect_b64 vcc, -1, 0
	v_cndmask_b32_e32 v199, v199, v1, vcc
	v_cndmask_b32_e32 v198, v198, v82, vcc
	v_cndmask_b32_e32 v241, v89, v83, vcc
	v_cndmask_b32_e32 v240, v88, v84, vcc
	v_lshl_add_u64 v[242:243], v[86:87], 0, v[160:161]
	s_add_i32 m0, s1, 0xc000
	ds_read_b128 v[208:211], v182
	ds_read_b128 v[212:215], v182 offset:1024
	ds_read_b128 v[216:219], v182 offset:2048
	ds_read_b128 v[220:223], v182 offset:3072
	ds_read_b128 v[224:227], v182 offset:4096
	ds_read_b128 v[228:231], v182 offset:5120
	ds_read_b128 v[232:235], v182 offset:6144
	ds_read_b128 v[236:239], v182 offset:7168
	global_load_lds_dwordx4 v[242:243], off
	v_lshl_add_u64 v[242:243], v[86:87], 0, v[162:163]
	s_add_i32 m0, s1, 0xe000
	s_nop 0
	global_load_lds_dwordx4 v[242:243], off
	s_waitcnt vmcnt(8)
	s_waitcnt lgkmcnt(0)
	s_barrier
	s_setprio 1
	s_waitcnt lgkmcnt(0)
	v_mfma_f32_16x16x32_bf16 v[102:105], v[94:97], v[208:211], 0
	v_mfma_f32_16x16x32_bf16 v[142:145], v[174:177], v[208:211], 0
	v_mfma_f32_16x16x32_bf16 v[62:65], v[94:97], v[216:219], 0
	v_mfma_f32_16x16x32_bf16 v[110:113], v[174:177], v[216:219], 0
	v_mfma_f32_16x16x32_bf16 v[46:49], v[94:97], v[224:227], 0
	v_mfma_f32_16x16x32_bf16 v[78:81], v[174:177], v[224:227], 0
	v_mfma_f32_16x16x32_bf16 v[38:41], v[94:97], v[232:235], 0
	v_mfma_f32_16x16x32_bf16 v[134:137], v[174:177], v[232:235], 0
	v_mfma_f32_16x16x32_bf16 v[102:105], v[98:101], v[212:215], v[102:105]
	v_mfma_f32_16x16x32_bf16 v[142:145], v[186:189], v[212:215], v[142:145]
	v_mfma_f32_16x16x32_bf16 v[62:65], v[98:101], v[220:223], v[62:65]
	v_mfma_f32_16x16x32_bf16 v[110:113], v[186:189], v[220:223], v[110:113]
	v_mfma_f32_16x16x32_bf16 v[46:49], v[98:101], v[228:231], v[46:49]
	v_mfma_f32_16x16x32_bf16 v[78:81], v[186:189], v[228:231], v[78:81]
	v_mfma_f32_16x16x32_bf16 v[38:41], v[98:101], v[236:239], v[38:41]
	v_mfma_f32_16x16x32_bf16 v[134:137], v[186:189], v[236:239], v[134:137]
	s_setprio 0
	s_setprio 1
	v_mfma_f32_16x16x32_bf16 v[138:141], v[190:193], v[208:211], 0
	v_mfma_f32_16x16x32_bf16 v[90:93], v[200:203], v[208:211], 0
	v_mfma_f32_16x16x32_bf16 v[106:109], v[190:193], v[216:219], 0
	v_mfma_f32_16x16x32_bf16 v[50:53], v[200:203], v[216:219], 0
	v_mfma_f32_16x16x32_bf16 v[74:77], v[190:193], v[224:227], 0
	v_mfma_f32_16x16x32_bf16 v[42:45], v[200:203], v[224:227], 0
	v_mfma_f32_16x16x32_bf16 v[130:133], v[190:193], v[232:235], 0
	v_mfma_f32_16x16x32_bf16 v[34:37], v[200:203], v[232:235], 0
	v_mfma_f32_16x16x32_bf16 v[138:141], v[194:197], v[212:215], v[138:141]
	v_mfma_f32_16x16x32_bf16 v[90:93], v[204:207], v[212:215], v[90:93]
	v_mfma_f32_16x16x32_bf16 v[106:109], v[194:197], v[220:223], v[106:109]
	v_mfma_f32_16x16x32_bf16 v[50:53], v[204:207], v[220:223], v[50:53]
	v_mfma_f32_16x16x32_bf16 v[74:77], v[194:197], v[228:231], v[74:77]
	v_mfma_f32_16x16x32_bf16 v[42:45], v[204:207], v[228:231], v[42:45]
	v_mfma_f32_16x16x32_bf16 v[130:133], v[194:197], v[236:239], v[130:133]
	v_mfma_f32_16x16x32_bf16 v[34:37], v[204:207], v[236:239], v[34:37]
	s_setprio 0
	s_barrier
	s_add_i32 s8, s55, s0
	v_lshl_add_u64 v[242:243], v[240:241], 0, v[150:151]
	s_mov_b32 m0, s8
	ds_read_b128 v[208:211], v182 offset:16384
	ds_read_b128 v[212:215], v182 offset:17408
	ds_read_b128 v[216:219], v182 offset:18432
	ds_read_b128 v[220:223], v182 offset:19456
	ds_read_b128 v[224:227], v182 offset:20480
	ds_read_b128 v[228:231], v182 offset:21504
	ds_read_b128 v[232:235], v182 offset:22528
	ds_read_b128 v[236:239], v182 offset:23552
	global_load_lds_dwordx4 v[242:243], off
	v_lshl_add_u64 v[244:245], v[240:241], 0, v[152:153]
	s_add_i32 m0, s8, 0x2000
	v_lshl_add_u64 v[246:247], v[240:241], 0, s[22:23]
	s_add_i32 s8, s56, s0
	global_load_lds_dwordx4 v[244:245], off
	v_lshl_add_u64 v[248:249], v[246:247], 0, v[150:151]
	s_mov_b32 m0, s8
	v_lshl_add_u64 v[246:247], v[246:247], 0, v[152:153]
	global_load_lds_dwordx4 v[248:249], off
	s_add_i32 m0, s8, 0x2000
	v_lshl_add_u64 v[248:249], v[198:199], 0, v[152:153]
	global_load_lds_dwordx4 v[246:247], off
	v_lshl_add_u64 v[246:247], v[198:199], 0, v[150:151]
	s_mov_b32 m0, s1
	s_nop 0
	global_load_lds_dwordx4 v[246:247], off
	s_mov_b32 m0, s2
	s_nop 0
	global_load_lds_dwordx4 v[248:249], off
	s_waitcnt vmcnt(8)
	s_waitcnt lgkmcnt(0)
	s_barrier
	s_setprio 1
	s_waitcnt lgkmcnt(0)
	v_mfma_f32_16x16x32_bf16 v[30:33], v[94:97], v[208:211], 0
	v_mfma_f32_16x16x32_bf16 v[126:129], v[174:177], v[208:211], 0
	v_mfma_f32_16x16x32_bf16 v[22:25], v[94:97], v[216:219], 0
	v_mfma_f32_16x16x32_bf16 v[70:73], v[174:177], v[216:219], 0
	v_mfma_f32_16x16x32_bf16 v[14:17], v[94:97], v[224:227], 0
	v_mfma_f32_16x16x32_bf16 v[66:69], v[174:177], v[224:227], 0
	v_mfma_f32_16x16x32_bf16 v[6:9], v[94:97], v[232:235], 0
	v_mfma_f32_16x16x32_bf16 v[30:33], v[98:101], v[212:215], v[30:33]
	v_mfma_f32_16x16x32_bf16 v[126:129], v[186:189], v[212:215], v[126:129]
	v_mfma_f32_16x16x32_bf16 v[22:25], v[98:101], v[220:223], v[22:25]
	v_mfma_f32_16x16x32_bf16 v[70:73], v[186:189], v[220:223], v[70:73]
	v_mfma_f32_16x16x32_bf16 v[14:17], v[98:101], v[228:231], v[14:17]
	v_mfma_f32_16x16x32_bf16 v[66:69], v[186:189], v[228:231], v[66:69]
	v_mfma_f32_16x16x32_bf16 v[6:9], v[98:101], v[236:239], v[6:9]
	v_mfma_f32_16x16x32_bf16 v[94:97], v[174:177], v[232:235], 0
	v_mfma_f32_16x16x32_bf16 v[94:97], v[186:189], v[236:239], v[94:97]
	s_setprio 0
	s_setprio 1
	v_mfma_f32_16x16x32_bf16 v[26:29], v[200:203], v[208:211], 0
	v_mfma_f32_16x16x32_bf16 v[58:61], v[190:193], v[216:219], 0
	v_mfma_f32_16x16x32_bf16 v[18:21], v[200:203], v[216:219], 0
	v_mfma_f32_16x16x32_bf16 v[54:57], v[190:193], v[224:227], 0
	v_mfma_f32_16x16x32_bf16 v[10:13], v[200:203], v[224:227], 0
	v_mfma_f32_16x16x32_bf16 v[114:117], v[190:193], v[232:235], 0
	v_mfma_f32_16x16x32_bf16 v[2:5], v[200:203], v[232:235], 0
	v_mfma_f32_16x16x32_bf16 v[98:101], v[190:193], v[208:211], 0
	v_mfma_f32_16x16x32_bf16 v[26:29], v[204:207], v[212:215], v[26:29]
	v_mfma_f32_16x16x32_bf16 v[58:61], v[194:197], v[220:223], v[58:61]
	v_mfma_f32_16x16x32_bf16 v[18:21], v[204:207], v[220:223], v[18:21]
	v_mfma_f32_16x16x32_bf16 v[54:57], v[194:197], v[228:231], v[54:57]
	v_mfma_f32_16x16x32_bf16 v[10:13], v[204:207], v[228:231], v[10:13]
	v_mfma_f32_16x16x32_bf16 v[114:117], v[194:197], v[236:239], v[114:117]
	v_mfma_f32_16x16x32_bf16 v[2:5], v[204:207], v[236:239], v[2:5]
	v_mfma_f32_16x16x32_bf16 v[98:101], v[194:197], v[212:215], v[98:101]
	s_setprio 0
	s_barrier
	s_add_i32 s8, 0, 0x18000
	v_add_u32_e32 v85, s8, v180
	s_add_i32 s9, 0, 0x1c000
	ds_read_b128 v[118:121], v85
	ds_read_b128 v[122:125], v85 offset:1024
	ds_read_b128 v[174:177], v85 offset:2048
	ds_read_b128 v[186:189], v85 offset:3072
	v_add_u32_e32 v85, s9, v180
	ds_read_b128 v[190:193], v85
	ds_read_b128 v[194:197], v85 offset:1024
	ds_read_b128 v[200:203], v85 offset:2048
	ds_read_b128 v[204:207], v85 offset:3072
	v_lshl_add_u64 v[198:199], v[198:199], 0, s[22:23]
	s_mov_b32 m0, s3
	v_lshl_add_u64 v[250:251], v[198:199], 0, v[150:151]
	ds_read_b128 v[208:211], v182 offset:32768
	ds_read_b128 v[212:215], v182 offset:33792
	ds_read_b128 v[216:219], v182 offset:34816
	ds_read_b128 v[220:223], v182 offset:35840
	ds_read_b128 v[224:227], v182 offset:36864
	ds_read_b128 v[228:231], v182 offset:37888
	ds_read_b128 v[232:235], v182 offset:38912
	ds_read_b128 v[236:239], v182 offset:39936
	global_load_lds_dwordx4 v[250:251], off
	v_lshl_add_u64 v[198:199], v[198:199], 0, v[152:153]
	s_mov_b32 m0, s21
	s_nop 0
	global_load_lds_dwordx4 v[198:199], off
	s_waitcnt vmcnt(8)
	s_waitcnt lgkmcnt(0)
	s_barrier
	s_setprio 1
	s_waitcnt lgkmcnt(0)
	v_mfma_f32_16x16x32_bf16 v[102:105], v[118:121], v[208:211], v[102:105]
	v_mfma_f32_16x16x32_bf16 v[142:145], v[174:177], v[208:211], v[142:145]
	v_mfma_f32_16x16x32_bf16 v[62:65], v[118:121], v[216:219], v[62:65]
	v_mfma_f32_16x16x32_bf16 v[110:113], v[174:177], v[216:219], v[110:113]
	v_mfma_f32_16x16x32_bf16 v[46:49], v[118:121], v[224:227], v[46:49]
	v_mfma_f32_16x16x32_bf16 v[78:81], v[174:177], v[224:227], v[78:81]
	v_mfma_f32_16x16x32_bf16 v[38:41], v[118:121], v[232:235], v[38:41]
	v_mfma_f32_16x16x32_bf16 v[134:137], v[174:177], v[232:235], v[134:137]
	v_mfma_f32_16x16x32_bf16 v[102:105], v[122:125], v[212:215], v[102:105]
	v_mfma_f32_16x16x32_bf16 v[142:145], v[186:189], v[212:215], v[142:145]
	v_mfma_f32_16x16x32_bf16 v[62:65], v[122:125], v[220:223], v[62:65]
	v_mfma_f32_16x16x32_bf16 v[110:113], v[186:189], v[220:223], v[110:113]
	v_mfma_f32_16x16x32_bf16 v[46:49], v[122:125], v[228:231], v[46:49]
	v_mfma_f32_16x16x32_bf16 v[78:81], v[186:189], v[228:231], v[78:81]
	v_mfma_f32_16x16x32_bf16 v[38:41], v[122:125], v[236:239], v[38:41]
	v_mfma_f32_16x16x32_bf16 v[134:137], v[186:189], v[236:239], v[134:137]
	s_setprio 0
	s_setprio 1
	v_mfma_f32_16x16x32_bf16 v[138:141], v[190:193], v[208:211], v[138:141]
	v_mfma_f32_16x16x32_bf16 v[90:93], v[200:203], v[208:211], v[90:93]
	v_mfma_f32_16x16x32_bf16 v[106:109], v[190:193], v[216:219], v[106:109]
	v_mfma_f32_16x16x32_bf16 v[50:53], v[200:203], v[216:219], v[50:53]
	v_mfma_f32_16x16x32_bf16 v[74:77], v[190:193], v[224:227], v[74:77]
	v_mfma_f32_16x16x32_bf16 v[42:45], v[200:203], v[224:227], v[42:45]
	v_mfma_f32_16x16x32_bf16 v[130:133], v[190:193], v[232:235], v[130:133]
	v_mfma_f32_16x16x32_bf16 v[34:37], v[200:203], v[232:235], v[34:37]
	v_mfma_f32_16x16x32_bf16 v[138:141], v[194:197], v[212:215], v[138:141]
	v_mfma_f32_16x16x32_bf16 v[90:93], v[204:207], v[212:215], v[90:93]
	v_mfma_f32_16x16x32_bf16 v[106:109], v[194:197], v[220:223], v[106:109]
	v_mfma_f32_16x16x32_bf16 v[50:53], v[204:207], v[220:223], v[50:53]
	v_mfma_f32_16x16x32_bf16 v[74:77], v[194:197], v[228:231], v[74:77]
	v_mfma_f32_16x16x32_bf16 v[42:45], v[204:207], v[228:231], v[42:45]
	v_mfma_f32_16x16x32_bf16 v[130:133], v[194:197], v[236:239], v[130:133]
	v_mfma_f32_16x16x32_bf16 v[34:37], v[204:207], v[236:239], v[34:37]
	s_setprio 0
	s_barrier
	s_add_i32 s8, s8, s0
	v_lshl_add_u64 v[198:199], v[242:243], 0, s[26:27]
	s_mov_b32 m0, s8
	ds_read_b128 v[208:211], v182 offset:49152
	ds_read_b128 v[212:215], v182 offset:50176
	ds_read_b128 v[216:219], v182 offset:51200
	ds_read_b128 v[220:223], v182 offset:52224
	ds_read_b128 v[224:227], v182 offset:53248
	ds_read_b128 v[228:231], v182 offset:54272
	ds_read_b128 v[232:235], v182 offset:55296
	ds_read_b128 v[236:239], v182 offset:56320
	global_load_lds_dwordx4 v[198:199], off
	v_lshl_add_u64 v[198:199], v[244:245], 0, s[26:27]
	s_add_i32 m0, s8, 0x2000
	s_add_i32 s8, s9, s0
	global_load_lds_dwordx4 v[198:199], off
	v_lshl_add_u64 v[198:199], v[240:241], 0, s[28:29]
	v_lshl_add_u64 v[240:241], v[198:199], 0, v[150:151]
	s_mov_b32 m0, s8
	v_lshl_add_u64 v[198:199], v[198:199], 0, v[152:153]
	global_load_lds_dwordx4 v[240:241], off
	s_add_i32 m0, s8, 0x2000
	s_nop 0
	global_load_lds_dwordx4 v[198:199], off
	v_lshl_add_u64 v[198:199], v[246:247], 0, s[26:27]
	s_mov_b32 m0, s35
	s_nop 0
	global_load_lds_dwordx4 v[198:199], off
	v_lshl_add_u64 v[198:199], v[248:249], 0, s[26:27]
	s_mov_b32 m0, s50
	s_nop 0
	global_load_lds_dwordx4 v[198:199], off
	s_waitcnt vmcnt(8)
	s_waitcnt lgkmcnt(0)
	s_barrier
	s_setprio 1
	s_waitcnt lgkmcnt(0)
	v_mfma_f32_16x16x32_bf16 v[30:33], v[118:121], v[208:211], v[30:33]
	v_mfma_f32_16x16x32_bf16 v[126:129], v[174:177], v[208:211], v[126:129]
	v_mfma_f32_16x16x32_bf16 v[22:25], v[118:121], v[216:219], v[22:25]
	v_mfma_f32_16x16x32_bf16 v[70:73], v[174:177], v[216:219], v[70:73]
	v_mfma_f32_16x16x32_bf16 v[14:17], v[118:121], v[224:227], v[14:17]
	v_mfma_f32_16x16x32_bf16 v[66:69], v[174:177], v[224:227], v[66:69]
	v_mfma_f32_16x16x32_bf16 v[6:9], v[118:121], v[232:235], v[6:9]
	v_mfma_f32_16x16x32_bf16 v[94:97], v[174:177], v[232:235], v[94:97]
	v_mfma_f32_16x16x32_bf16 v[30:33], v[122:125], v[212:215], v[30:33]
	v_mfma_f32_16x16x32_bf16 v[126:129], v[186:189], v[212:215], v[126:129]
	v_mfma_f32_16x16x32_bf16 v[22:25], v[122:125], v[220:223], v[22:25]
	v_mfma_f32_16x16x32_bf16 v[70:73], v[186:189], v[220:223], v[70:73]
	v_mfma_f32_16x16x32_bf16 v[14:17], v[122:125], v[228:231], v[14:17]
	v_mfma_f32_16x16x32_bf16 v[66:69], v[186:189], v[228:231], v[66:69]
	v_mfma_f32_16x16x32_bf16 v[6:9], v[122:125], v[236:239], v[6:9]
	v_mfma_f32_16x16x32_bf16 v[118:121], v[186:189], v[236:239], v[94:97]
	s_setprio 0
	s_setprio 1
	v_mfma_f32_16x16x32_bf16 v[94:97], v[190:193], v[208:211], v[98:101]
	v_mfma_f32_16x16x32_bf16 v[122:125], v[194:197], v[212:215], v[94:97]
	v_mfma_f32_16x16x32_bf16 v[26:29], v[200:203], v[208:211], v[26:29]
	v_mfma_f32_16x16x32_bf16 v[58:61], v[190:193], v[216:219], v[58:61]
	v_mfma_f32_16x16x32_bf16 v[18:21], v[200:203], v[216:219], v[18:21]
	v_mfma_f32_16x16x32_bf16 v[54:57], v[190:193], v[224:227], v[54:57]
	v_mfma_f32_16x16x32_bf16 v[10:13], v[200:203], v[224:227], v[10:13]
	v_mfma_f32_16x16x32_bf16 v[94:97], v[190:193], v[232:235], v[114:117]
	v_mfma_f32_16x16x32_bf16 v[2:5], v[200:203], v[232:235], v[2:5]
	v_mfma_f32_16x16x32_bf16 v[26:29], v[204:207], v[212:215], v[26:29]
	v_mfma_f32_16x16x32_bf16 v[58:61], v[194:197], v[220:223], v[58:61]
	v_mfma_f32_16x16x32_bf16 v[18:21], v[204:207], v[220:223], v[18:21]
	v_mfma_f32_16x16x32_bf16 v[54:57], v[194:197], v[228:231], v[54:57]
	v_mfma_f32_16x16x32_bf16 v[10:13], v[204:207], v[228:231], v[10:13]
	v_mfma_f32_16x16x32_bf16 v[114:117], v[194:197], v[236:239], v[94:97]
	v_mfma_f32_16x16x32_bf16 v[2:5], v[204:207], v[236:239], v[2:5]
	s_setprio 0
	s_barrier
	s_add_i32 s7, s7, 2
	v_lshl_add_u64 v[86:87], v[86:87], 0, s[40:41]
	s_cmp_gt_u32 s7, 13
	v_lshl_add_u64 v[88:89], v[88:89], 0, s[40:41]
	s_cbranch_scc0 .LBB0_1252
	s_branch .Lpeel_exit_4

.Lpeel_exit_4:
	s_and_b64 vcc, exec, s[30:31]
	s_cbranch_vccz .LBB0_1255
	s_barrier

.LBB0_1382:
	s_ashr_i32 s35, s34, 31
	s_lshl_b64 s[42:43], s[34:35], 20
	s_ashr_i32 s37, s36, 31
	s_ashr_i32 s31, s30, 31
	v_lshl_add_u64 v[0:1], v[168:169], 0, s[42:43]
	s_lshl_b64 s[42:43], s[36:37], 7
	s_lshl_b64 s[44:45], s[30:31], 20
	v_lshl_add_u64 v[182:183], v[0:1], 0, s[42:43]
	v_lshl_add_u64 v[0:1], v[160:161], 0, s[44:45]
	v_lshl_add_u64 v[184:185], v[0:1], 0, s[42:43]
	v_mov_b32_e32 v64, 0
	v_cndmask_b32_e64 v129, v5, v183, s[38:39]
	v_cndmask_b32_e64 v128, v4, v182, s[38:39]
	v_cndmask_b32_e64 v131, v3, v185, s[38:39]
	v_cndmask_b32_e64 v130, v2, v184, s[38:39]
	s_add_i32 s31, s5, -2
	v_lshl_add_u64 v[132:133], v[4:5], 0, s[18:19]
	v_lshl_add_u64 v[134:135], v[2:3], 0, s[24:25]
	s_mov_b32 s35, 0
	v_add_u32_e32 v148, s57, v194
	v_add_u32_e32 v197, s58, v194
	ds_read_b128 v[136:139], v148
	ds_read_b128 v[140:143], v148 offset:1024
	ds_read_b128 v[144:147], v148 offset:2048
	ds_read_b128 v[148:151], v148 offset:3072
	ds_read_b128 v[152:155], v197
	ds_read_b128 v[156:159], v197 offset:1024
	ds_read_b128 v[186:189], v197 offset:2048
	ds_read_b128 v[198:201], v197 offset:3072
	s_cmp_eq_u32 s31, s35
	v_lshl_add_u64 v[190:191], v[132:133], 0, s[26:27]
	s_cselect_b64 vcc, -1, 0
	s_add_i32 s35, s35, 2
	v_cndmask_b32_e32 v191, v191, v129, vcc
	v_cndmask_b32_e32 v190, v190, v128, vcc
	v_cndmask_b32_e32 v235, v135, v131, vcc
	v_cndmask_b32_e32 v234, v134, v130, vcc
	v_lshl_add_u64 v[236:237], v[132:133], 0, v[178:179]
	s_add_i32 m0, s47, 0xc000
	ds_read_b128 v[202:205], v195
	ds_read_b128 v[206:209], v195 offset:1024
	ds_read_b128 v[210:213], v195 offset:2048
	ds_read_b128 v[214:217], v195 offset:3072
	ds_read_b128 v[218:221], v195 offset:4096
	ds_read_b128 v[222:225], v195 offset:5120
	ds_read_b128 v[226:229], v195 offset:6144
	ds_read_b128 v[230:233], v195 offset:7168
	global_load_lds_dwordx4 v[236:237], off
	v_lshl_add_u64 v[236:237], v[132:133], 0, v[180:181]
	s_add_i32 m0, s47, 0xe000
	s_nop 0
	global_load_lds_dwordx4 v[236:237], off
	s_waitcnt vmcnt(8)
	s_waitcnt lgkmcnt(0)
	s_barrier
	s_setprio 1
	s_waitcnt lgkmcnt(0)
	v_mfma_f32_16x16x32_bf16 v[60:63], v[136:139], v[202:205], 0
	v_mfma_f32_16x16x32_bf16 v[56:59], v[144:147], v[202:205], 0
	v_mfma_f32_16x16x32_bf16 v[52:55], v[136:139], v[210:213], 0
	v_mfma_f32_16x16x32_bf16 v[48:51], v[144:147], v[210:213], 0
	v_mfma_f32_16x16x32_bf16 v[44:47], v[136:139], v[218:221], 0
	v_mfma_f32_16x16x32_bf16 v[40:43], v[144:147], v[218:221], 0
	v_mfma_f32_16x16x32_bf16 v[36:39], v[136:139], v[226:229], 0
	v_mfma_f32_16x16x32_bf16 v[32:35], v[144:147], v[226:229], 0
	v_mfma_f32_16x16x32_bf16 v[60:63], v[140:143], v[206:209], v[60:63]
	v_mfma_f32_16x16x32_bf16 v[56:59], v[148:151], v[206:209], v[56:59]
	v_mfma_f32_16x16x32_bf16 v[52:55], v[140:143], v[214:217], v[52:55]
	v_mfma_f32_16x16x32_bf16 v[48:51], v[148:151], v[214:217], v[48:51]
	v_mfma_f32_16x16x32_bf16 v[44:47], v[140:143], v[222:225], v[44:47]
	v_mfma_f32_16x16x32_bf16 v[40:43], v[148:151], v[222:225], v[40:43]
	v_mfma_f32_16x16x32_bf16 v[36:39], v[140:143], v[230:233], v[36:39]
	v_mfma_f32_16x16x32_bf16 v[32:35], v[148:151], v[230:233], v[32:35]
	s_setprio 0
	s_setprio 1
	v_mfma_f32_16x16x32_bf16 v[28:31], v[152:155], v[202:205], 0
	v_mfma_f32_16x16x32_bf16 v[24:27], v[186:189], v[202:205], 0
	v_mfma_f32_16x16x32_bf16 v[20:23], v[152:155], v[210:213], 0
	v_mfma_f32_16x16x32_bf16 v[16:19], v[186:189], v[210:213], 0
	v_mfma_f32_16x16x32_bf16 v[12:15], v[152:155], v[218:221], 0
	v_mfma_f32_16x16x32_bf16 v[8:11], v[186:189], v[218:221], 0
	v_mfma_f32_16x16x32_bf16 v[4:7], v[152:155], v[226:229], 0
	v_mfma_f32_16x16x32_bf16 v[0:3], v[186:189], v[226:229], 0
	v_mfma_f32_16x16x32_bf16 v[28:31], v[156:159], v[206:209], v[28:31]
	v_mfma_f32_16x16x32_bf16 v[24:27], v[198:201], v[206:209], v[24:27]
	v_mfma_f32_16x16x32_bf16 v[20:23], v[156:159], v[214:217], v[20:23]
	v_mfma_f32_16x16x32_bf16 v[16:19], v[198:201], v[214:217], v[16:19]
	v_mfma_f32_16x16x32_bf16 v[12:15], v[156:159], v[222:225], v[12:15]
	v_mfma_f32_16x16x32_bf16 v[8:11], v[198:201], v[222:225], v[8:11]
	v_mfma_f32_16x16x32_bf16 v[4:7], v[156:159], v[230:233], v[4:7]
	v_mfma_f32_16x16x32_bf16 v[0:3], v[198:201], v[230:233], v[0:3]
	s_setprio 0
	s_barrier
	s_add_i32 s37, s57, s3
	v_lshl_add_u64 v[236:237], v[234:235], 0, v[162:163]
	s_mov_b32 m0, s37
	ds_read_b128 v[202:205], v195 offset:16384
	ds_read_b128 v[206:209], v195 offset:17408
	ds_read_b128 v[210:213], v195 offset:18432
	ds_read_b128 v[214:217], v195 offset:19456
	ds_read_b128 v[218:221], v195 offset:20480
	ds_read_b128 v[222:225], v195 offset:21504
	ds_read_b128 v[226:229], v195 offset:22528
	ds_read_b128 v[230:233], v195 offset:23552
	global_load_lds_dwordx4 v[236:237], off
	v_lshl_add_u64 v[238:239], v[234:235], 0, v[164:165]
	s_add_i32 m0, s37, 0x2000
	v_lshl_add_u64 v[240:241], v[234:235], 0, s[12:13]
	s_add_i32 s37, s58, s3
	global_load_lds_dwordx4 v[238:239], off
	v_lshl_add_u64 v[242:243], v[240:241], 0, v[162:163]
	s_mov_b32 m0, s37
	v_lshl_add_u64 v[240:241], v[240:241], 0, v[164:165]
	global_load_lds_dwordx4 v[242:243], off
	s_add_i32 m0, s37, 0x2000
	v_lshl_add_u64 v[242:243], v[190:191], 0, v[164:165]
	global_load_lds_dwordx4 v[240:241], off
	v_lshl_add_u64 v[240:241], v[190:191], 0, v[162:163]
	s_mov_b32 m0, s47
	s_nop 0
	global_load_lds_dwordx4 v[240:241], off
	s_mov_b32 m0, s48
	s_nop 0
	global_load_lds_dwordx4 v[242:243], off
	s_waitcnt vmcnt(8)
	s_waitcnt lgkmcnt(0)
	s_barrier
	s_setprio 1
	s_waitcnt lgkmcnt(0)
	v_mfma_f32_16x16x32_bf16 v[124:127], v[136:139], v[202:205], 0
	v_mfma_f32_16x16x32_bf16 v[120:123], v[144:147], v[202:205], 0
	v_mfma_f32_16x16x32_bf16 v[116:119], v[136:139], v[210:213], 0
	v_mfma_f32_16x16x32_bf16 v[112:115], v[144:147], v[210:213], 0
	v_mfma_f32_16x16x32_bf16 v[108:111], v[136:139], v[218:221], 0
	v_mfma_f32_16x16x32_bf16 v[104:107], v[144:147], v[218:221], 0
	v_mfma_f32_16x16x32_bf16 v[100:103], v[136:139], v[226:229], 0
	v_mfma_f32_16x16x32_bf16 v[96:99], v[144:147], v[226:229], 0
	v_mfma_f32_16x16x32_bf16 v[124:127], v[140:143], v[206:209], v[124:127]
	v_mfma_f32_16x16x32_bf16 v[120:123], v[148:151], v[206:209], v[120:123]
	v_mfma_f32_16x16x32_bf16 v[116:119], v[140:143], v[214:217], v[116:119]
	v_mfma_f32_16x16x32_bf16 v[112:115], v[148:151], v[214:217], v[112:115]
	v_mfma_f32_16x16x32_bf16 v[108:111], v[140:143], v[222:225], v[108:111]
	v_mfma_f32_16x16x32_bf16 v[104:107], v[148:151], v[222:225], v[104:107]
	v_mfma_f32_16x16x32_bf16 v[100:103], v[140:143], v[230:233], v[100:103]
	v_mfma_f32_16x16x32_bf16 v[96:99], v[148:151], v[230:233], v[96:99]
	s_setprio 0
	s_setprio 1
	v_mfma_f32_16x16x32_bf16 v[92:95], v[152:155], v[202:205], 0
	v_mfma_f32_16x16x32_bf16 v[88:91], v[186:189], v[202:205], 0
	v_mfma_f32_16x16x32_bf16 v[84:87], v[152:155], v[210:213], 0
	v_mfma_f32_16x16x32_bf16 v[80:83], v[186:189], v[210:213], 0
	v_mfma_f32_16x16x32_bf16 v[76:79], v[152:155], v[218:221], 0
	v_mfma_f32_16x16x32_bf16 v[72:75], v[186:189], v[218:221], 0
	v_mfma_f32_16x16x32_bf16 v[68:71], v[152:155], v[226:229], 0
	v_mfma_f32_16x16x32_bf16 v[64:67], v[186:189], v[226:229], 0
	v_mfma_f32_16x16x32_bf16 v[92:95], v[156:159], v[206:209], v[92:95]
	v_mfma_f32_16x16x32_bf16 v[88:91], v[198:201], v[206:209], v[88:91]
	v_mfma_f32_16x16x32_bf16 v[84:87], v[156:159], v[214:217], v[84:87]
	v_mfma_f32_16x16x32_bf16 v[80:83], v[198:201], v[214:217], v[80:83]
	v_mfma_f32_16x16x32_bf16 v[76:79], v[156:159], v[222:225], v[76:79]
	v_mfma_f32_16x16x32_bf16 v[72:75], v[198:201], v[222:225], v[72:75]
	v_mfma_f32_16x16x32_bf16 v[68:71], v[156:159], v[230:233], v[68:71]
	v_mfma_f32_16x16x32_bf16 v[64:67], v[198:201], v[230:233], v[64:67]
	s_setprio 0
	s_barrier
	s_add_i32 s37, 0, 0x18000
	s_add_i32 s41, 0, 0x1c000
	v_add_u32_e32 v148, s37, v194
	v_add_u32_e32 v197, s41, v194
	ds_read_b128 v[136:139], v148
	ds_read_b128 v[140:143], v148 offset:1024
	ds_read_b128 v[144:147], v148 offset:2048
	ds_read_b128 v[148:151], v148 offset:3072
	ds_read_b128 v[152:155], v197
	ds_read_b128 v[156:159], v197 offset:1024
	ds_read_b128 v[186:189], v197 offset:2048
	ds_read_b128 v[198:201], v197 offset:3072
	v_lshl_add_u64 v[190:191], v[190:191], 0, s[12:13]
	s_mov_b32 m0, s49
	v_lshl_add_u64 v[244:245], v[190:191], 0, v[162:163]
	ds_read_b128 v[202:205], v195 offset:32768
	ds_read_b128 v[206:209], v195 offset:33792
	ds_read_b128 v[210:213], v195 offset:34816
	ds_read_b128 v[214:217], v195 offset:35840
	ds_read_b128 v[218:221], v195 offset:36864
	ds_read_b128 v[222:225], v195 offset:37888
	ds_read_b128 v[226:229], v195 offset:38912
	ds_read_b128 v[230:233], v195 offset:39936
	global_load_lds_dwordx4 v[244:245], off
	v_lshl_add_u64 v[190:191], v[190:191], 0, v[164:165]
	s_mov_b32 m0, s50
	s_nop 0
	global_load_lds_dwordx4 v[190:191], off
	s_waitcnt vmcnt(8)
	s_waitcnt lgkmcnt(0)
	s_barrier
	s_setprio 1
	s_waitcnt lgkmcnt(0)
	v_mfma_f32_16x16x32_bf16 v[60:63], v[136:139], v[202:205], v[60:63]
	v_mfma_f32_16x16x32_bf16 v[56:59], v[144:147], v[202:205], v[56:59]
	v_mfma_f32_16x16x32_bf16 v[52:55], v[136:139], v[210:213], v[52:55]
	v_mfma_f32_16x16x32_bf16 v[48:51], v[144:147], v[210:213], v[48:51]
	v_mfma_f32_16x16x32_bf16 v[44:47], v[136:139], v[218:221], v[44:47]
	v_mfma_f32_16x16x32_bf16 v[40:43], v[144:147], v[218:221], v[40:43]
	v_mfma_f32_16x16x32_bf16 v[36:39], v[136:139], v[226:229], v[36:39]
	v_mfma_f32_16x16x32_bf16 v[32:35], v[144:147], v[226:229], v[32:35]
	v_mfma_f32_16x16x32_bf16 v[60:63], v[140:143], v[206:209], v[60:63]
	v_mfma_f32_16x16x32_bf16 v[56:59], v[148:151], v[206:209], v[56:59]
	v_mfma_f32_16x16x32_bf16 v[52:55], v[140:143], v[214:217], v[52:55]
	v_mfma_f32_16x16x32_bf16 v[48:51], v[148:151], v[214:217], v[48:51]
	v_mfma_f32_16x16x32_bf16 v[44:47], v[140:143], v[222:225], v[44:47]
	v_mfma_f32_16x16x32_bf16 v[40:43], v[148:151], v[222:225], v[40:43]
	v_mfma_f32_16x16x32_bf16 v[36:39], v[140:143], v[230:233], v[36:39]
	v_mfma_f32_16x16x32_bf16 v[32:35], v[148:151], v[230:233], v[32:35]
	s_setprio 0
	s_setprio 1
	v_mfma_f32_16x16x32_bf16 v[28:31], v[152:155], v[202:205], v[28:31]
	v_mfma_f32_16x16x32_bf16 v[24:27], v[186:189], v[202:205], v[24:27]
	v_mfma_f32_16x16x32_bf16 v[20:23], v[152:155], v[210:213], v[20:23]
	v_mfma_f32_16x16x32_bf16 v[16:19], v[186:189], v[210:213], v[16:19]
	v_mfma_f32_16x16x32_bf16 v[12:15], v[152:155], v[218:221], v[12:15]
	v_mfma_f32_16x16x32_bf16 v[8:11], v[186:189], v[218:221], v[8:11]
	v_mfma_f32_16x16x32_bf16 v[4:7], v[152:155], v[226:229], v[4:7]
	v_mfma_f32_16x16x32_bf16 v[0:3], v[186:189], v[226:229], v[0:3]
	v_mfma_f32_16x16x32_bf16 v[28:31], v[156:159], v[206:209], v[28:31]
	v_mfma_f32_16x16x32_bf16 v[24:27], v[198:201], v[206:209], v[24:27]
	v_mfma_f32_16x16x32_bf16 v[20:23], v[156:159], v[214:217], v[20:23]
	v_mfma_f32_16x16x32_bf16 v[16:19], v[198:201], v[214:217], v[16:19]
	v_mfma_f32_16x16x32_bf16 v[12:15], v[156:159], v[222:225], v[12:15]
	v_mfma_f32_16x16x32_bf16 v[8:11], v[198:201], v[222:225], v[8:11]
	v_mfma_f32_16x16x32_bf16 v[4:7], v[156:159], v[230:233], v[4:7]
	v_mfma_f32_16x16x32_bf16 v[0:3], v[198:201], v[230:233], v[0:3]
	s_setprio 0
	s_barrier
	s_add_i32 s37, s37, s3
	v_lshl_add_u64 v[190:191], v[236:237], 0, s[16:17]
	s_mov_b32 m0, s37
	ds_read_b128 v[202:205], v195 offset:49152
	ds_read_b128 v[206:209], v195 offset:50176
	ds_read_b128 v[210:213], v195 offset:51200
	ds_read_b128 v[214:217], v195 offset:52224
	ds_read_b128 v[218:221], v195 offset:53248
	ds_read_b128 v[222:225], v195 offset:54272
	ds_read_b128 v[226:229], v195 offset:55296
	ds_read_b128 v[230:233], v195 offset:56320
	global_load_lds_dwordx4 v[190:191], off
	v_lshl_add_u64 v[190:191], v[238:239], 0, s[16:17]
	s_add_i32 m0, s37, 0x2000
	s_add_i32 s37, s41, s3
	global_load_lds_dwordx4 v[190:191], off
	v_lshl_add_u64 v[190:191], v[234:235], 0, s[18:19]
	v_lshl_add_u64 v[234:235], v[190:191], 0, v[162:163]
	s_mov_b32 m0, s37
	v_lshl_add_u64 v[190:191], v[190:191], 0, v[164:165]
	global_load_lds_dwordx4 v[234:235], off
	s_add_i32 m0, s37, 0x2000
	s_nop 0
	global_load_lds_dwordx4 v[190:191], off
	v_lshl_add_u64 v[190:191], v[240:241], 0, s[16:17]
	s_mov_b32 m0, s52
	s_nop 0
	global_load_lds_dwordx4 v[190:191], off
	v_lshl_add_u64 v[190:191], v[242:243], 0, s[16:17]
	s_mov_b32 m0, s53
	s_nop 0
	global_load_lds_dwordx4 v[190:191], off
	s_waitcnt vmcnt(8)
	s_waitcnt lgkmcnt(0)
	s_barrier
	s_setprio 1
	s_waitcnt lgkmcnt(0)
	v_mfma_f32_16x16x32_bf16 v[124:127], v[136:139], v[202:205], v[124:127]
	v_mfma_f32_16x16x32_bf16 v[120:123], v[144:147], v[202:205], v[120:123]
	v_mfma_f32_16x16x32_bf16 v[116:119], v[136:139], v[210:213], v[116:119]
	v_mfma_f32_16x16x32_bf16 v[112:115], v[144:147], v[210:213], v[112:115]
	v_mfma_f32_16x16x32_bf16 v[108:111], v[136:139], v[218:221], v[108:111]
	v_mfma_f32_16x16x32_bf16 v[104:107], v[144:147], v[218:221], v[104:107]
	v_mfma_f32_16x16x32_bf16 v[100:103], v[136:139], v[226:229], v[100:103]
	v_mfma_f32_16x16x32_bf16 v[96:99], v[144:147], v[226:229], v[96:99]
	v_mfma_f32_16x16x32_bf16 v[124:127], v[140:143], v[206:209], v[124:127]
	v_mfma_f32_16x16x32_bf16 v[120:123], v[148:151], v[206:209], v[120:123]
	v_mfma_f32_16x16x32_bf16 v[116:119], v[140:143], v[214:217], v[116:119]
	v_mfma_f32_16x16x32_bf16 v[112:115], v[148:151], v[214:217], v[112:115]
	v_mfma_f32_16x16x32_bf16 v[108:111], v[140:143], v[222:225], v[108:111]
	v_mfma_f32_16x16x32_bf16 v[104:107], v[148:151], v[222:225], v[104:107]
	v_mfma_f32_16x16x32_bf16 v[100:103], v[140:143], v[230:233], v[100:103]
	v_mfma_f32_16x16x32_bf16 v[96:99], v[148:151], v[230:233], v[96:99]
	s_setprio 0
	s_setprio 1
	v_mfma_f32_16x16x32_bf16 v[92:95], v[152:155], v[202:205], v[92:95]
	v_mfma_f32_16x16x32_bf16 v[88:91], v[186:189], v[202:205], v[88:91]
	v_mfma_f32_16x16x32_bf16 v[84:87], v[152:155], v[210:213], v[84:87]
	v_mfma_f32_16x16x32_bf16 v[80:83], v[186:189], v[210:213], v[80:83]
	v_mfma_f32_16x16x32_bf16 v[76:79], v[152:155], v[218:221], v[76:79]
	v_mfma_f32_16x16x32_bf16 v[72:75], v[186:189], v[218:221], v[72:75]
	v_mfma_f32_16x16x32_bf16 v[68:71], v[152:155], v[226:229], v[68:71]
	v_mfma_f32_16x16x32_bf16 v[64:67], v[186:189], v[226:229], v[64:67]
	v_mfma_f32_16x16x32_bf16 v[92:95], v[156:159], v[206:209], v[92:95]
	v_mfma_f32_16x16x32_bf16 v[88:91], v[198:201], v[206:209], v[88:91]
	v_mfma_f32_16x16x32_bf16 v[84:87], v[156:159], v[214:217], v[84:87]
	v_mfma_f32_16x16x32_bf16 v[80:83], v[198:201], v[214:217], v[80:83]
	v_mfma_f32_16x16x32_bf16 v[76:79], v[156:159], v[222:225], v[76:79]
	v_mfma_f32_16x16x32_bf16 v[72:75], v[198:201], v[222:225], v[72:75]
	v_mfma_f32_16x16x32_bf16 v[68:71], v[156:159], v[230:233], v[68:71]
	v_mfma_f32_16x16x32_bf16 v[64:67], v[198:201], v[230:233], v[64:67]
	s_setprio 0
	s_barrier
	v_lshl_add_u64 v[132:133], v[132:133], 0, s[24:25]
	s_cmp_ge_i32 s35, s5
	v_lshl_add_u64 v[134:135], v[134:135], 0, s[24:25]
	s_cbranch_scc0 .LBB0_1383
	s_branch .Lpeel_exit_5

.Lpeel_exit_5:
	s_and_b64 vcc, exec, s[20:21]
	s_cbranch_vccz .LBB0_1386
	s_barrier
